# v043 + NA local tile select-before-exp: the in-window key of each (j, j+16) accumulator pair is selected before exp2 (other is exp2(-1e30)=0), halving exp/row-sum VALU; raw bias as accumulator init (n
# speedup vs baseline: 1.0153x; 1.0153x over previous
;     ...
;     for (int gh = 0; gh < 4 / GPB; ++gh) {
;         f32x4 S[GPB][4];
; #pragma unroll
;         for (int kb = 0; kb < 4; ++kb) {
;             const bf16x8 kf0 = *(const LAS bf16x8*)(kb0 + (16 * kb) * 128 + kx0), kf1 = *(const LAS bf16x8*)(kb0 + (16 * kb) * 128 + kx1);
; #pragma unroll
;             for (int gi = 0; gi < GPB; ++gi) { S[gi][kb] = __builtin_amdgcn_mfma_f32_16x16x32_bf16(kf0, qf[GPB * gh + gi][0], cinit, 0, 0, 0);
;                 S[gi][kb] = __builtin_amdgcn_mfma_f32_16x16x32_bf16(kf1, qf[GPB * gh + gi][1], S[gi][kb], 0, 0, 0); } }
;         bf16x8 pf[GPB][2];
; #pragma unroll
;         for (int gi = 0; gi < GPB; ++gi) {
; __device__ __forceinline__ void na_phase(LAS unsigned char* lds, const bf16_t* Q, const bf16_t* K, const bf16_t* V, bf16_t* Ob, const float* rpb, float negb) {
;     ...
;         const int kr_lo = min(max(4 * rq - 4, 0), 120), kr_hi = min(max(4 * rq - 1, 0), 120) + 8;
;         const int NT = 4 + (isctx ? 0 : kr_hi - kr_lo);
;         const DmaLane dl = dma_lane(DM, hp * 128, w, lane);
;     ...
;         dma_tile<2>(lds, K, V, NA_ROW0(0), DM, dl, w);
;         dma_tile<2>(lds + NA_BUF, K, V, NA_ROW0(1), DM, dl, w);
;         dma_tile<2>(lds + 2 * NA_BUF, K, V, NA_ROW0(2), DM, dl, w);
;         for (int i = tid; i < 2 * 465; i += 512) { const int h2 = i / 465, e = i - h2 * 465; tab[h2 * 512 + e] = rpb[(2 * hp + h2) * 465 + e] * LOG2E; }
;         const int r = 4 * rq + (w & 3);
;         const size_t qrow0 = isctx ? (size_t)(MLAT + b * NCTX + (w & 3) * 64) : (size_t)(b * SEQ + r * 64);
;         bf16x8 qf[4][2];
; #pragma unroll
;         for (int grp = 0; grp < 4; ++grp)
; #pragma unroll
;             for (int ds = 0; ds < 2; ++ds) qf[grp][ds] = *(const bf16x8*)(Q + (qrow0 + 16 * grp + l15) * DM + head * 64 + 32 * ds + 8 * g);
;         f32x4 O[4][4]; float ls[4];
; #pragma unroll
;         for (int grp = 0; grp < 4; ++grp) { ls[grp] = 0.f;
; #pragma unroll
;             for (int db = 0; db < 4; ++db) O[grp][db] = (f32x4){0.f, 0.f, 0.f, 0.f}; }
;         const int r0w = min(max(r - 4, 0), 120);
;         drain_wait();
;         for (int t = 0; t < 4; ++t) {
;             dma_tile<2>(lds + ((t + 3) & 3) * NA_BUF, K, V, NA_ROW0(t + 3), DM, dl, w);
;             const LAS unsigned char* buf = lds + (t & 3) * NA_BUF;
;             full_tile<0, 1, 2>(O, ls, qf, negb, buf + hh * 8192, buf + 2 * 8192 + hh * 8192, lane, 0);
.LBB0_377:
	s_or_b64 exec, exec, s[96:97]
	v_sub_u32_e64 v4, s68, 1 clamp
	s_lshl_b32 s61, s6, 13
	v_readfirstlane_b32 s6, v4
	s_max_u32 s60, s68, 4
	s_min_u32 s6, s6, 0x78
	s_lshl_b32 s7, s7, 1
	v_readlane_b32 s59, v240, 49
	s_sub_i32 s6, s6, s60
	s_add_i32 s59, s7, s59
	s_add_i32 s66, s6, 16
	s_and_b64 s[6:7], exec, s[0:1]
	s_mov_b32 s33, s93
	s_cselect_b32 s93, 4, s66
	s_or_b32 s6, s68, s2
	v_readlane_b32 s7, v240, 48
	s_lshl_b32 s66, s6, 6
	s_or_b32 s7, s82, s7
	s_or_b32 s66, s61, s66
	s_and_b64 s[0:1], exec, s[0:1]
	s_cselect_b32 s0, s7, s66
	v_or_b32_e32 v154, s0, v199
	s_lshl_b32 s0, s59, 6
	s_ashr_i32 s1, s0, 31
	v_lshl_add_u64 v[28:29], s[0:1], 1, v[112:113]
	v_lshlrev_b64 v[122:123], 11, v[154:155]
	v_lshl_add_u64 v[8:9], v[28:29], 0, v[122:123]
	global_load_dwordx4 v[4:7], v[8:9], off
	s_nop 0
	global_load_dwordx4 v[8:11], v[8:9], off offset:64
	s_max_i32 s97, s6, 4
	s_or_b32 s59, s94, 0x60000
	v_or_b32_e32 v12, 16, v154
	v_mov_b32_e32 v13, v155
	v_or_b32_e32 v20, 32, v154
	v_mov_b32_e32 v21, v155
	v_or_b32_e32 v154, 48, v154
	s_add_u32 s6, s67, s59
	v_lshlrev_b64 v[120:121], 11, v[12:13]
	v_lshlrev_b64 v[118:119], 11, v[20:21]
	v_lshlrev_b64 v[116:117], 11, v[154:155]
	s_addc_u32 s7, s4, s95
	v_lshl_add_u64 v[16:17], v[28:29], 0, v[120:121]
	v_lshl_add_u64 v[24:25], v[28:29], 0, v[118:119]
	v_lshl_add_u64 v[32:33], v[28:29], 0, v[116:117]
	s_add_u32 s94, s5, s59
	global_load_dwordx4 v[12:15], v[16:17], off
	s_nop 0
	global_load_dwordx4 v[16:19], v[16:17], off offset:64
	s_nop 0
	global_load_dwordx4 v[20:23], v[24:25], off
	s_nop 0
	global_load_dwordx4 v[24:27], v[24:25], off offset:64
	s_nop 0
	global_load_dwordx4 v[28:31], v[32:33], off
	s_nop 0
	global_load_dwordx4 v[32:35], v[32:33], off offset:64
	s_waitcnt vmcnt(0)
	s_waitcnt lgkmcnt(0)
	s_barrier
	s_addc_u32 s95, s58, s95
	s_add_i32 s59, s69, 0x18000
	s_mov_b32 s76, m0
	s_mov_b32 m0, s59
	s_nop 0
	global_load_lds_dwordx4 v221, s[6:7]
	s_mov_b32 m0, s76
	s_add_i32 s66, s69, 0x1c000
	s_mov_b32 s59, m0
	s_mov_b32 m0, s66
	s_nop 0
	global_load_lds_dwordx4 v222, s[94:95]
	s_mov_b32 m0, s59
	s_add_i32 s59, s69, 0x1a000
	s_mov_b32 s66, m0
	s_mov_b32 m0, s59
	s_nop 0
	global_load_lds_dwordx4 v223, s[6:7]
	s_mov_b32 m0, s66
	s_add_i32 s6, s69, 0x1e000
	s_mov_b32 s7, m0
	s_mov_b32 m0, s6
	s_nop 0
	global_load_lds_dwordx4 v224, s[94:95]
	s_mov_b32 m0, s7
	v_mov_b32_e32 v48, 0
	v_mov_b32_e32 v49, 0
	v_mov_b32_e32 v50, 0
	v_mov_b32_e32 v51, 0
	v_mov_b32_e32 v44, 0
	v_mov_b32_e32 v45, 0
	v_mov_b32_e32 v46, 0
	v_mov_b32_e32 v47, 0
	v_mov_b32_e32 v40, 0
	v_mov_b32_e32 v41, 0
	v_mov_b32_e32 v42, 0
	v_mov_b32_e32 v43, 0
	v_mov_b32_e32 v36, 0
	v_mov_b32_e32 v37, 0
	v_mov_b32_e32 v38, 0
	v_mov_b32_e32 v39, 0
	v_mov_b32_e32 v126, 0
	v_mov_b32_e32 v64, 0
	v_mov_b32_e32 v65, 0
	v_mov_b32_e32 v66, 0
	v_mov_b32_e32 v67, 0
	v_mov_b32_e32 v60, 0
	v_mov_b32_e32 v61, 0
	v_mov_b32_e32 v62, 0
	v_mov_b32_e32 v63, 0
	v_mov_b32_e32 v56, 0
	v_mov_b32_e32 v57, 0
	v_mov_b32_e32 v58, 0
	v_mov_b32_e32 v59, 0
	v_mov_b32_e32 v52, 0
	v_mov_b32_e32 v53, 0
	v_mov_b32_e32 v54, 0
	v_mov_b32_e32 v55, 0
	v_mov_b32_e32 v127, 0
	v_mov_b32_e32 v80, 0
	v_mov_b32_e32 v81, 0
	v_mov_b32_e32 v82, 0
	v_mov_b32_e32 v83, 0
	v_mov_b32_e32 v76, 0
	v_mov_b32_e32 v77, 0
	v_mov_b32_e32 v78, 0
	v_mov_b32_e32 v79, 0
	v_mov_b32_e32 v72, 0
	v_mov_b32_e32 v73, 0
	v_mov_b32_e32 v74, 0
	v_mov_b32_e32 v75, 0
	v_mov_b32_e32 v68, 0
	v_mov_b32_e32 v69, 0
	v_mov_b32_e32 v70, 0
	v_mov_b32_e32 v71, 0
	v_mov_b32_e32 v124, 0
	v_mov_b32_e32 v84, 0
	v_mov_b32_e32 v85, 0
	v_mov_b32_e32 v86, 0
	v_mov_b32_e32 v87, 0
	v_mov_b32_e32 v92, 0
	v_mov_b32_e32 v93, 0
	v_mov_b32_e32 v94, 0
	v_mov_b32_e32 v95, 0
	v_mov_b32_e32 v88, 0
	v_mov_b32_e32 v89, 0
	v_mov_b32_e32 v90, 0
	v_mov_b32_e32 v91, 0
	v_mov_b32_e32 v96, 0
	v_mov_b32_e32 v97, 0
	v_mov_b32_e32 v98, 0
	v_mov_b32_e32 v99, 0
	v_mov_b32_e32 v125, 0
	s_mov_b32 s96, 4
	s_lshl_b32 s6, s60, 6
	s_addk_i32 s6, 0xff00
	s_add_u32 s94, s61, s6
	s_addc_u32 s95, 0, 0
	s_mov_b32 vcc_lo, 0
	s_add_i32 s76, s65, 0
	v_add_u32_e32 v144, s76, v111
	v_add3_u32 v193, s76, v210, v205
	v_add_u32_e32 v145, v144, v204
	v_add_u32_e32 v144, v144, v203
	ds_read_b128 v[160:163], v144
	ds_read_b128 v[164:167], v145
	ds_read_b128 v[168:171], v144 offset:2048
	ds_read_b128 v[172:175], v145 offset:2048
	ds_read_b128 v[128:131], v144 offset:4096
	ds_read_b128 v[132:135], v145 offset:4096
	ds_read_b128 v[136:139], v144 offset:6144
	ds_read_b128 v[140:143], v145 offset:6144
	v_add_u32_e32 v158, v193, v206
	v_add_u32_e32 v159, v193, v207
	v_add_u32_e32 v192, v193, v208
	v_add_u32_e32 v193, v193, v209
	s_waitcnt lgkmcnt(4)
	v_mfma_f32_16x16x32_bf16 v[228:231], v[160:163], v[4:7], v[0:3]
	v_mfma_f32_16x16x32_bf16 v[232:235], v[168:171], v[4:7], v[0:3]
	v_mfma_f32_16x16x32_bf16 v[228:231], v[164:167], v[8:11], v[228:231]
	v_mfma_f32_16x16x32_bf16 v[232:235], v[172:175], v[8:11], v[232:235]
	ds_read_b64_tr_b16 v[176:177], v158 offset:16384
	ds_read_b64_tr_b16 v[178:179], v158 offset:18432
	ds_read_b64_tr_b16 v[180:181], v159 offset:16384
	ds_read_b64_tr_b16 v[182:183], v159 offset:18432
	ds_read_b64_tr_b16 v[184:185], v192 offset:16384
	ds_read_b64_tr_b16 v[186:187], v192 offset:18432
	ds_read_b64_tr_b16 v[188:189], v193 offset:16384
	ds_read_b64_tr_b16 v[190:191], v193 offset:18432
	v_mfma_f32_16x16x32_bf16 v[236:239], v[160:163], v[12:15], v[0:3]
	v_exp_f32_e32 v228, v228
	v_exp_f32_e32 v229, v229
	v_exp_f32_e32 v230, v230
	v_add_f32_e32 v154, v228, v229
	v_mfma_f32_16x16x32_bf16 v[104:107], v[168:171], v[12:15], v[0:3]
	v_exp_f32_e32 v231, v231
	v_add_f32_e32 v154, v154, v230
	v_exp_f32_e32 v232, v232
	v_add_f32_e32 v154, v154, v231
	v_mfma_f32_16x16x32_bf16 v[236:239], v[164:167], v[16:19], v[236:239]
	v_exp_f32_e32 v233, v233
	v_add_f32_e32 v154, v154, v232
	v_exp_f32_e32 v234, v234
	v_add_f32_e32 v154, v154, v233
	v_cvt_pk_bf16_f32 v228, v228, v229
	v_mfma_f32_16x16x32_bf16 v[104:107], v[172:175], v[16:19], v[104:107]
	v_exp_f32_e32 v235, v235
	v_add_f32_e32 v154, v154, v234
	v_cvt_pk_bf16_f32 v229, v230, v231
	v_cvt_pk_bf16_f32 v230, v232, v233
	v_cvt_pk_bf16_f32 v231, v234, v235
	v_add_f32_e32 v154, v154, v235
	v_add_f32_e32 v126, v126, v154
	s_waitcnt lgkmcnt(0)
; #define LAS __attribute__((address_space(3)))
; __device__ __forceinline__ s16x4 vtr(const LAS unsigned char* p) { return __builtin_bit_cast(s16x4, __builtin_amdgcn_ds_read_tr16_b64_v4i16((LAS v4i16_t*)p)); }
; __device__ __forceinline__ bf16x8 cat8(s16x4 a, s16x4 b) { return (bf16x8){a[0], a[1], a[2], a[3], b[0], b[1], b[2], b[3]}; }
; __device__ __forceinline__ bf16x8 pack8(const f32x4& a, const f32x4& b) { u32x4 w; w.x = pkbf(a[0], a[1]); w.y = pkbf(a[2], a[3]); w.z = pkbf(b[0], b[1]); w.w = pkbf(b[2], b[3]); return __builtin_bit_cast(bf16x8, w); }
;     ...
;     for (int gh = 0; gh < 4 / GPB; ++gh) {
;         f32x4 S[GPB][4];
; #pragma unroll
;         for (int kb = 0; kb < 4; ++kb) {
;             const bf16x8 kf0 = *(const LAS bf16x8*)(kb0 + (16 * kb) * 128 + kx0), kf1 = *(const LAS bf16x8*)(kb0 + (16 * kb) * 128 + kx1);
; #pragma unroll
;             for (int gi = 0; gi < GPB; ++gi) { S[gi][kb] = __builtin_amdgcn_mfma_f32_16x16x32_bf16(kf0, qf[GPB * gh + gi][0], cinit, 0, 0, 0);
;                 S[gi][kb] = __builtin_amdgcn_mfma_f32_16x16x32_bf16(kf1, qf[GPB * gh + gi][1], S[gi][kb], 0, 0, 0); } }
;         bf16x8 pf[GPB][2];
; #pragma unroll
;         for (int gi = 0; gi < GPB; ++gi) {
;             if (MASK) {
; #pragma unroll
;                 for (int kb = 0; kb < 4; ++kb)
; #pragma unroll
;                     for (int i = 0; i < 4; ++i) { const int rel = rel0 + 16 * kb + 4 * g + i; S[gi][kb][i] = ((unsigned)(rel + 128) > 256u) ? NEGBIG : S[gi][kb][i]; }
;             }
;             ls[GPB * gh + gi] += exp_step<4>(S[gi]);
;             pf[gi][0] = pack8(S[gi][0], S[gi][1]); pf[gi][1] = pack8(S[gi][2], S[gi][3]);
;         }
; #pragma unroll
;         for (int kc = 0; kc < 2; ++kc)
; #pragma unroll
;             for (int db = 0; db < 4; ++db) {
;                 const LAS unsigned char* va = vrow + ((db ^ swz) << 5) + (32 * kc) * 128;
;                 const bf16x8 vf = cat8(vtr(va), vtr(va + 16 * 128));
; #pragma unroll
;                 for (int gi = 0; gi < GPB; ++gi) O[GPB * gh + gi][db] = __builtin_amdgcn_mfma_f32_16x16x32_bf16(vf, pf[gi][kc], O[GPB * gh + gi][db], 0, 0, 0);
;             }
	v_mfma_f32_16x16x32_bf16 v[244:247], v[160:163], v[20:23], v[0:3]
	v_exp_f32_e32 v236, v236
	v_exp_f32_e32 v237, v237
	v_mfma_f32_16x16x32_bf16 v[248:251], v[168:171], v[20:23], v[0:3]
	v_exp_f32_e32 v238, v238
	v_add_f32_e32 v154, v236, v237
	v_mfma_f32_16x16x32_bf16 v[244:247], v[164:167], v[24:27], v[244:247]
	v_exp_f32_e32 v239, v239
	v_add_f32_e32 v154, v154, v238
	v_mfma_f32_16x16x32_bf16 v[248:251], v[172:175], v[24:27], v[248:251]
	v_exp_f32_e32 v104, v104
	v_add_f32_e32 v154, v154, v239
	v_mfma_f32_16x16x32_bf16 v[48:51], v[176:179], v[228:231], v[48:51]
	v_exp_f32_e32 v105, v105
	v_add_f32_e32 v154, v154, v104
	v_mfma_f32_16x16x32_bf16 v[44:47], v[180:183], v[228:231], v[44:47]
	v_exp_f32_e32 v106, v106
	v_add_f32_e32 v154, v154, v105
	v_cvt_pk_bf16_f32 v236, v236, v237
	v_mfma_f32_16x16x32_bf16 v[40:43], v[184:187], v[228:231], v[40:43]
	v_exp_f32_e32 v107, v107
	v_add_f32_e32 v154, v154, v106
	v_cvt_pk_bf16_f32 v237, v238, v239
	v_mfma_f32_16x16x32_bf16 v[36:39], v[188:191], v[228:231], v[36:39]
	v_cvt_pk_bf16_f32 v238, v104, v105
	v_cvt_pk_bf16_f32 v239, v106, v107
	v_add_f32_e32 v154, v154, v107
	v_add_f32_e32 v127, v127, v154
	v_mfma_f32_16x16x32_bf16 v[228:231], v[160:163], v[28:31], v[0:3]
	v_exp_f32_e32 v244, v244
	v_exp_f32_e32 v245, v245
	v_mfma_f32_16x16x32_bf16 v[232:235], v[168:171], v[28:31], v[0:3]
	v_exp_f32_e32 v246, v246
	v_add_f32_e32 v154, v244, v245
	v_mfma_f32_16x16x32_bf16 v[228:231], v[164:167], v[32:35], v[228:231]
	v_exp_f32_e32 v247, v247
	v_add_f32_e32 v154, v154, v246
	v_mfma_f32_16x16x32_bf16 v[232:235], v[172:175], v[32:35], v[232:235]
	v_exp_f32_e32 v248, v248
	v_add_f32_e32 v154, v154, v247
	v_mfma_f32_16x16x32_bf16 v[64:67], v[176:179], v[236:239], v[64:67]
	v_exp_f32_e32 v249, v249
	v_add_f32_e32 v154, v154, v248
	v_mfma_f32_16x16x32_bf16 v[60:63], v[180:183], v[236:239], v[60:63]
	v_exp_f32_e32 v250, v250
	v_add_f32_e32 v154, v154, v249
	v_cvt_pk_bf16_f32 v244, v244, v245
	v_mfma_f32_16x16x32_bf16 v[56:59], v[184:187], v[236:239], v[56:59]
	v_exp_f32_e32 v251, v251
	v_add_f32_e32 v154, v154, v250
	v_cvt_pk_bf16_f32 v245, v246, v247
	v_mfma_f32_16x16x32_bf16 v[52:55], v[188:191], v[236:239], v[52:55]
	v_cvt_pk_bf16_f32 v246, v248, v249
	v_cvt_pk_bf16_f32 v247, v250, v251
	v_add_f32_e32 v154, v154, v251
	v_add_f32_e32 v124, v124, v154
	ds_read_b64_tr_b16 v[160:161], v158 offset:20480
	ds_read_b64_tr_b16 v[162:163], v158 offset:22528
	ds_read_b64_tr_b16 v[164:165], v159 offset:20480
	ds_read_b64_tr_b16 v[166:167], v159 offset:22528
	ds_read_b64_tr_b16 v[168:169], v192 offset:20480
	ds_read_b64_tr_b16 v[170:171], v192 offset:22528
	ds_read_b64_tr_b16 v[172:173], v193 offset:20480
	ds_read_b64_tr_b16 v[174:175], v193 offset:22528
	v_mfma_f32_16x16x32_bf16 v[236:239], v[128:131], v[4:7], v[0:3]
	v_exp_f32_e32 v228, v228
	v_exp_f32_e32 v229, v229
	v_mfma_f32_16x16x32_bf16 v[104:107], v[136:139], v[4:7], v[0:3]
	v_exp_f32_e32 v230, v230
	v_add_f32_e32 v154, v228, v229
	v_mfma_f32_16x16x32_bf16 v[236:239], v[132:135], v[8:11], v[236:239]
	v_exp_f32_e32 v231, v231
	v_add_f32_e32 v154, v154, v230
	v_mfma_f32_16x16x32_bf16 v[104:107], v[140:143], v[8:11], v[104:107]
	v_exp_f32_e32 v232, v232
	v_add_f32_e32 v154, v154, v231
	v_mfma_f32_16x16x32_bf16 v[80:83], v[176:179], v[244:247], v[80:83]
	v_exp_f32_e32 v233, v233
	v_add_f32_e32 v154, v154, v232
	v_mfma_f32_16x16x32_bf16 v[76:79], v[180:183], v[244:247], v[76:79]
	v_exp_f32_e32 v234, v234
	v_add_f32_e32 v154, v154, v233
	v_cvt_pk_bf16_f32 v228, v228, v229
	v_mfma_f32_16x16x32_bf16 v[72:75], v[184:187], v[244:247], v[72:75]
	v_exp_f32_e32 v235, v235
	v_add_f32_e32 v154, v154, v234
	v_cvt_pk_bf16_f32 v229, v230, v231
	v_mfma_f32_16x16x32_bf16 v[68:71], v[188:191], v[244:247], v[68:71]
	v_cvt_pk_bf16_f32 v230, v232, v233
	v_cvt_pk_bf16_f32 v231, v234, v235
	v_add_f32_e32 v154, v154, v235
	v_add_f32_e32 v125, v125, v154
	v_mfma_f32_16x16x32_bf16 v[244:247], v[128:131], v[12:15], v[0:3]
	v_exp_f32_e32 v236, v236
	v_exp_f32_e32 v237, v237
	v_mfma_f32_16x16x32_bf16 v[248:251], v[136:139], v[12:15], v[0:3]
	v_exp_f32_e32 v238, v238
	v_add_f32_e32 v154, v236, v237
	v_mfma_f32_16x16x32_bf16 v[244:247], v[132:135], v[16:19], v[244:247]
	v_exp_f32_e32 v239, v239
	v_add_f32_e32 v154, v154, v238
	v_mfma_f32_16x16x32_bf16 v[248:251], v[140:143], v[16:19], v[248:251]
	v_exp_f32_e32 v104, v104
	v_add_f32_e32 v154, v154, v239
	v_mfma_f32_16x16x32_bf16 v[84:87], v[176:179], v[228:231], v[84:87]
	v_exp_f32_e32 v105, v105
	v_add_f32_e32 v154, v154, v104
	v_mfma_f32_16x16x32_bf16 v[92:95], v[180:183], v[228:231], v[92:95]
	v_exp_f32_e32 v106, v106
	v_add_f32_e32 v154, v154, v105
	v_cvt_pk_bf16_f32 v236, v236, v237
	v_mfma_f32_16x16x32_bf16 v[88:91], v[184:187], v[228:231], v[88:91]
	v_exp_f32_e32 v107, v107
	v_add_f32_e32 v154, v154, v106
	v_cvt_pk_bf16_f32 v237, v238, v239
	v_mfma_f32_16x16x32_bf16 v[96:99], v[188:191], v[228:231], v[96:99]
	v_cvt_pk_bf16_f32 v238, v104, v105
	v_cvt_pk_bf16_f32 v239, v106, v107
	v_add_f32_e32 v154, v154, v107
	v_add_f32_e32 v126, v126, v154
	s_waitcnt lgkmcnt(0)
; #define LAS __attribute__((address_space(3)))
; __device__ __forceinline__ s16x4 vtr(const LAS unsigned char* p) { return __builtin_bit_cast(s16x4, __builtin_amdgcn_ds_read_tr16_b64_v4i16((LAS v4i16_t*)p)); }
;     ...
;     for (int gh = 0; gh < 4 / GPB; ++gh) {
;         f32x4 S[GPB][4];
; #pragma unroll
;         for (int kb = 0; kb < 4; ++kb) {
;             const bf16x8 kf0 = *(const LAS bf16x8*)(kb0 + (16 * kb) * 128 + kx0), kf1 = *(const LAS bf16x8*)(kb0 + (16 * kb) * 128 + kx1);
; #pragma unroll
;             for (int gi = 0; gi < GPB; ++gi) { S[gi][kb] = __builtin_amdgcn_mfma_f32_16x16x32_bf16(kf0, qf[GPB * gh + gi][0], cinit, 0, 0, 0);
;                 S[gi][kb] = __builtin_amdgcn_mfma_f32_16x16x32_bf16(kf1, qf[GPB * gh + gi][1], S[gi][kb], 0, 0, 0); } }
;         bf16x8 pf[GPB][2];
; #pragma unroll
;         for (int gi = 0; gi < GPB; ++gi) {
;             if (MASK) {
; #pragma unroll
;                 for (int kb = 0; kb < 4; ++kb)
; #pragma unroll
;                     for (int i = 0; i < 4; ++i) { const int rel = rel0 + 16 * kb + 4 * g + i; S[gi][kb][i] = ((unsigned)(rel + 128) > 256u) ? NEGBIG : S[gi][kb][i]; }
;             }
;             ls[GPB * gh + gi] += exp_step<4>(S[gi]);
;             pf[gi][0] = pack8(S[gi][0], S[gi][1]); pf[gi][1] = pack8(S[gi][2], S[gi][3]);
;         }
; #pragma unroll
;         for (int kc = 0; kc < 2; ++kc)
; #pragma unroll
;             for (int db = 0; db < 4; ++db) {
;                 const LAS unsigned char* va = vrow + ((db ^ swz) << 5) + (32 * kc) * 128;
;                 const bf16x8 vf = cat8(vtr(va), vtr(va + 16 * 128));
; #pragma unroll
;                 for (int gi = 0; gi < GPB; ++gi) O[GPB * gh + gi][db] = __builtin_amdgcn_mfma_f32_16x16x32_bf16(vf, pf[gi][kc], O[GPB * gh + gi][db], 0, 0, 0);
;             }
; __device__ __forceinline__ void na_phase(LAS unsigned char* lds, const bf16_t* Q, const bf16_t* K, const bf16_t* V, bf16_t* Ob, const float* rpb, float negb) {
;     ...
;         for (int t = 0; t < 4; ++t) {
;             dma_tile<2>(lds + ((t + 3) & 3) * NA_BUF, K, V, NA_ROW0(t + 3), DM, dl, w);
;             const LAS unsigned char* buf = lds + (t & 3) * NA_BUF;
;             full_tile<0, 1, 2>(O, ls, qf, negb, buf + hh * 8192, buf + 2 * 8192 + hh * 8192, lane, 0);
;             ring_wait<4>();
	v_mfma_f32_16x16x32_bf16 v[228:231], v[128:131], v[20:23], v[0:3]
	v_exp_f32_e32 v244, v244
	v_exp_f32_e32 v245, v245
	v_mfma_f32_16x16x32_bf16 v[232:235], v[136:139], v[20:23], v[0:3]
	v_exp_f32_e32 v246, v246
	v_add_f32_e32 v154, v244, v245
	v_mfma_f32_16x16x32_bf16 v[228:231], v[132:135], v[24:27], v[228:231]
	v_exp_f32_e32 v247, v247
	v_add_f32_e32 v154, v154, v246
	v_mfma_f32_16x16x32_bf16 v[232:235], v[140:143], v[24:27], v[232:235]
	v_exp_f32_e32 v248, v248
	v_add_f32_e32 v154, v154, v247
	v_mfma_f32_16x16x32_bf16 v[48:51], v[160:163], v[236:239], v[48:51]
	v_exp_f32_e32 v249, v249
	v_add_f32_e32 v154, v154, v248
	v_mfma_f32_16x16x32_bf16 v[44:47], v[164:167], v[236:239], v[44:47]
	v_exp_f32_e32 v250, v250
	v_add_f32_e32 v154, v154, v249
	v_cvt_pk_bf16_f32 v244, v244, v245
	v_mfma_f32_16x16x32_bf16 v[40:43], v[168:171], v[236:239], v[40:43]
	v_exp_f32_e32 v251, v251
	v_add_f32_e32 v154, v154, v250
	v_cvt_pk_bf16_f32 v245, v246, v247
	v_mfma_f32_16x16x32_bf16 v[36:39], v[172:175], v[236:239], v[36:39]
	v_cvt_pk_bf16_f32 v246, v248, v249
	v_cvt_pk_bf16_f32 v247, v250, v251
	v_add_f32_e32 v154, v154, v251
	v_add_f32_e32 v127, v127, v154
	v_mfma_f32_16x16x32_bf16 v[236:239], v[128:131], v[28:31], v[0:3]
	v_exp_f32_e32 v228, v228
	v_exp_f32_e32 v229, v229
	v_mfma_f32_16x16x32_bf16 v[104:107], v[136:139], v[28:31], v[0:3]
	v_exp_f32_e32 v230, v230
	v_add_f32_e32 v154, v228, v229
	v_mfma_f32_16x16x32_bf16 v[236:239], v[132:135], v[32:35], v[236:239]
	v_exp_f32_e32 v231, v231
	v_add_f32_e32 v154, v154, v230
	v_mfma_f32_16x16x32_bf16 v[104:107], v[140:143], v[32:35], v[104:107]
	v_exp_f32_e32 v232, v232
	v_add_f32_e32 v154, v154, v231
	v_mfma_f32_16x16x32_bf16 v[64:67], v[160:163], v[244:247], v[64:67]
	v_exp_f32_e32 v233, v233
	v_add_f32_e32 v154, v154, v232
	v_mfma_f32_16x16x32_bf16 v[60:63], v[164:167], v[244:247], v[60:63]
	v_exp_f32_e32 v234, v234
	v_add_f32_e32 v154, v154, v233
	v_cvt_pk_bf16_f32 v228, v228, v229
	v_mfma_f32_16x16x32_bf16 v[56:59], v[168:171], v[244:247], v[56:59]
	v_exp_f32_e32 v235, v235
	v_add_f32_e32 v154, v154, v234
	v_cvt_pk_bf16_f32 v229, v230, v231
	v_mfma_f32_16x16x32_bf16 v[52:55], v[172:175], v[244:247], v[52:55]
	v_cvt_pk_bf16_f32 v230, v232, v233
	v_cvt_pk_bf16_f32 v231, v234, v235
	v_add_f32_e32 v154, v154, v235
	v_add_f32_e32 v124, v124, v154
	v_mfma_f32_16x16x32_bf16 v[80:83], v[160:163], v[228:231], v[80:83]
	v_exp_f32_e32 v236, v236
	v_exp_f32_e32 v237, v237
	v_exp_f32_e32 v238, v238
	v_add_f32_e32 v154, v236, v237
	v_mfma_f32_16x16x32_bf16 v[76:79], v[164:167], v[228:231], v[76:79]
	v_exp_f32_e32 v239, v239
	v_add_f32_e32 v154, v154, v238
	v_exp_f32_e32 v104, v104
	v_add_f32_e32 v154, v154, v239
	v_mfma_f32_16x16x32_bf16 v[72:75], v[168:171], v[228:231], v[72:75]
	v_exp_f32_e32 v105, v105
	v_add_f32_e32 v154, v154, v104
	v_exp_f32_e32 v106, v106
	v_add_f32_e32 v154, v154, v105
	v_cvt_pk_bf16_f32 v236, v236, v237
	v_mfma_f32_16x16x32_bf16 v[68:71], v[172:175], v[228:231], v[68:71]
	v_exp_f32_e32 v107, v107
	v_add_f32_e32 v154, v154, v106
	v_cvt_pk_bf16_f32 v237, v238, v239
	v_cvt_pk_bf16_f32 v238, v104, v105
	v_cvt_pk_bf16_f32 v239, v106, v107
	v_add_f32_e32 v154, v154, v107
	v_add_f32_e32 v125, v125, v154
	v_mfma_f32_16x16x32_bf16 v[84:87], v[160:163], v[236:239], v[84:87]
	v_mfma_f32_16x16x32_bf16 v[92:95], v[164:167], v[236:239], v[92:95]
	v_mfma_f32_16x16x32_bf16 v[88:91], v[168:171], v[236:239], v[88:91]
	v_mfma_f32_16x16x32_bf16 v[96:99], v[172:175], v[236:239], v[96:99]
	s_waitcnt vmcnt(8)
	s_barrier
	s_cmp_lt_i32 s96, s93
	s_cselect_b32 s7, s95, 0
	s_cselect_b32 s6, s94, s82
	s_lshl_b64 s[6:7], s[6:7], 11
	s_add_u32 s76, s67, s6
	s_addc_u32 s77, s4, s7
	s_add_u32 s6, s5, s6
	s_addc_u32 s7, s58, s7
	s_add_i32 s59, s69, vcc_lo
	s_mov_b32 vcc_hi, m0
	s_mov_b32 m0, s59
	s_nop 0
	global_load_lds_dwordx4 v221, s[76:77]
	s_mov_b32 m0, vcc_hi
	s_add_i32 s66, s59, 0x4000
	s_mov_b32 vcc_hi, m0
	s_mov_b32 m0, s66
	s_nop 0
	global_load_lds_dwordx4 v222, s[6:7]
	s_mov_b32 m0, vcc_hi
	s_add_i32 s66, s59, 0x2000
	s_mov_b32 vcc_hi, m0
	s_mov_b32 m0, s66
	s_nop 0
	global_load_lds_dwordx4 v223, s[76:77]
	s_mov_b32 m0, vcc_hi
	s_addk_i32 s59, 0x6000
	s_mov_b32 s66, m0
	s_mov_b32 m0, s59
	s_nop 0
	global_load_lds_dwordx4 v224, s[6:7]
	s_mov_b32 m0, s66
	s_add_i32 s76, s65, vcc_lo
	s_add_i32 s76, s76, 0x8000
	v_add_u32_e32 v144, s76, v111
	v_add3_u32 v193, s76, v210, v205
	v_add_u32_e32 v145, v144, v204
	v_add_u32_e32 v144, v144, v203
	ds_read_b128 v[160:163], v144
	ds_read_b128 v[164:167], v145
	ds_read_b128 v[168:171], v144 offset:2048
	ds_read_b128 v[172:175], v145 offset:2048
	ds_read_b128 v[128:131], v144 offset:4096
	ds_read_b128 v[132:135], v145 offset:4096
	ds_read_b128 v[136:139], v144 offset:6144
	ds_read_b128 v[140:143], v145 offset:6144
	v_add_u32_e32 v158, v193, v206
	v_add_u32_e32 v159, v193, v207
	v_add_u32_e32 v192, v193, v208
	v_add_u32_e32 v193, v193, v209
	s_waitcnt lgkmcnt(4)
; #define LAS __attribute__((address_space(3)))
; __device__ __forceinline__ s16x4 vtr(const LAS unsigned char* p) { return __builtin_bit_cast(s16x4, __builtin_amdgcn_ds_read_tr16_b64_v4i16((LAS v4i16_t*)p)); }
; __device__ __forceinline__ bf16x8 cat8(s16x4 a, s16x4 b) { return (bf16x8){a[0], a[1], a[2], a[3], b[0], b[1], b[2], b[3]}; }
; __device__ __forceinline__ bf16x8 pack8(const f32x4& a, const f32x4& b) { u32x4 w; w.x = pkbf(a[0], a[1]); w.y = pkbf(a[2], a[3]); w.z = pkbf(b[0], b[1]); w.w = pkbf(b[2], b[3]); return __builtin_bit_cast(bf16x8, w); }
;     ...
;     for (int gh = 0; gh < 4 / GPB; ++gh) {
;         f32x4 S[GPB][4];
; #pragma unroll
;         for (int kb = 0; kb < 4; ++kb) {
;             const bf16x8 kf0 = *(const LAS bf16x8*)(kb0 + (16 * kb) * 128 + kx0), kf1 = *(const LAS bf16x8*)(kb0 + (16 * kb) * 128 + kx1);
; #pragma unroll
;             for (int gi = 0; gi < GPB; ++gi) { S[gi][kb] = __builtin_amdgcn_mfma_f32_16x16x32_bf16(kf0, qf[GPB * gh + gi][0], cinit, 0, 0, 0);
;                 S[gi][kb] = __builtin_amdgcn_mfma_f32_16x16x32_bf16(kf1, qf[GPB * gh + gi][1], S[gi][kb], 0, 0, 0); } }
;         bf16x8 pf[GPB][2];
; #pragma unroll
;         for (int gi = 0; gi < GPB; ++gi) {
;             if (MASK) {
; #pragma unroll
;                 for (int kb = 0; kb < 4; ++kb)
; #pragma unroll
;                     for (int i = 0; i < 4; ++i) { const int rel = rel0 + 16 * kb + 4 * g + i; S[gi][kb][i] = ((unsigned)(rel + 128) > 256u) ? NEGBIG : S[gi][kb][i]; }
;             }
;             ls[GPB * gh + gi] += exp_step<4>(S[gi]);
;             pf[gi][0] = pack8(S[gi][0], S[gi][1]); pf[gi][1] = pack8(S[gi][2], S[gi][3]);
;         }
; #pragma unroll
;         for (int kc = 0; kc < 2; ++kc)
; #pragma unroll
;             for (int db = 0; db < 4; ++db) {
;                 const LAS unsigned char* va = vrow + ((db ^ swz) << 5) + (32 * kc) * 128;
;                 const bf16x8 vf = cat8(vtr(va), vtr(va + 16 * 128));
; #pragma unroll
;                 for (int gi = 0; gi < GPB; ++gi) O[GPB * gh + gi][db] = __builtin_amdgcn_mfma_f32_16x16x32_bf16(vf, pf[gi][kc], O[GPB * gh + gi][db], 0, 0, 0);
;             }
	v_mfma_f32_16x16x32_bf16 v[228:231], v[160:163], v[4:7], v[0:3]
	v_mfma_f32_16x16x32_bf16 v[232:235], v[168:171], v[4:7], v[0:3]
	v_mfma_f32_16x16x32_bf16 v[228:231], v[164:167], v[8:11], v[228:231]
	v_mfma_f32_16x16x32_bf16 v[232:235], v[172:175], v[8:11], v[232:235]
	ds_read_b64_tr_b16 v[176:177], v158 offset:16384
	ds_read_b64_tr_b16 v[178:179], v158 offset:18432
	ds_read_b64_tr_b16 v[180:181], v159 offset:16384
	ds_read_b64_tr_b16 v[182:183], v159 offset:18432
	ds_read_b64_tr_b16 v[184:185], v192 offset:16384
	ds_read_b64_tr_b16 v[186:187], v192 offset:18432
	ds_read_b64_tr_b16 v[188:189], v193 offset:16384
	ds_read_b64_tr_b16 v[190:191], v193 offset:18432
	v_mfma_f32_16x16x32_bf16 v[236:239], v[160:163], v[12:15], v[0:3]
	v_exp_f32_e32 v228, v228
	v_exp_f32_e32 v229, v229
	v_exp_f32_e32 v230, v230
	v_add_f32_e32 v154, v228, v229
	v_mfma_f32_16x16x32_bf16 v[104:107], v[168:171], v[12:15], v[0:3]
	v_exp_f32_e32 v231, v231
	v_add_f32_e32 v154, v154, v230
	v_exp_f32_e32 v232, v232
	v_add_f32_e32 v154, v154, v231
	v_mfma_f32_16x16x32_bf16 v[236:239], v[164:167], v[16:19], v[236:239]
	v_exp_f32_e32 v233, v233
	v_add_f32_e32 v154, v154, v232
	v_exp_f32_e32 v234, v234
	v_add_f32_e32 v154, v154, v233
	v_cvt_pk_bf16_f32 v228, v228, v229
	v_mfma_f32_16x16x32_bf16 v[104:107], v[172:175], v[16:19], v[104:107]
	v_exp_f32_e32 v235, v235
	v_add_f32_e32 v154, v154, v234
	v_cvt_pk_bf16_f32 v229, v230, v231
	v_cvt_pk_bf16_f32 v230, v232, v233
	v_cvt_pk_bf16_f32 v231, v234, v235
	v_add_f32_e32 v154, v154, v235
	v_add_f32_e32 v126, v126, v154
	s_waitcnt lgkmcnt(0)
	v_mfma_f32_16x16x32_bf16 v[244:247], v[160:163], v[20:23], v[0:3]
	v_exp_f32_e32 v236, v236
	v_exp_f32_e32 v237, v237
	v_mfma_f32_16x16x32_bf16 v[248:251], v[168:171], v[20:23], v[0:3]
	v_exp_f32_e32 v238, v238
	v_add_f32_e32 v154, v236, v237
	v_mfma_f32_16x16x32_bf16 v[244:247], v[164:167], v[24:27], v[244:247]
	v_exp_f32_e32 v239, v239
	v_add_f32_e32 v154, v154, v238
	v_mfma_f32_16x16x32_bf16 v[248:251], v[172:175], v[24:27], v[248:251]
	v_exp_f32_e32 v104, v104
	v_add_f32_e32 v154, v154, v239
	v_mfma_f32_16x16x32_bf16 v[48:51], v[176:179], v[228:231], v[48:51]
	v_exp_f32_e32 v105, v105
	v_add_f32_e32 v154, v154, v104
	v_mfma_f32_16x16x32_bf16 v[44:47], v[180:183], v[228:231], v[44:47]
	v_exp_f32_e32 v106, v106
	v_add_f32_e32 v154, v154, v105
	v_cvt_pk_bf16_f32 v236, v236, v237
	v_mfma_f32_16x16x32_bf16 v[40:43], v[184:187], v[228:231], v[40:43]
	v_exp_f32_e32 v107, v107
	v_add_f32_e32 v154, v154, v106
	v_cvt_pk_bf16_f32 v237, v238, v239
	v_mfma_f32_16x16x32_bf16 v[36:39], v[188:191], v[228:231], v[36:39]
	v_cvt_pk_bf16_f32 v238, v104, v105
	v_cvt_pk_bf16_f32 v239, v106, v107
	v_add_f32_e32 v154, v154, v107
	v_add_f32_e32 v127, v127, v154
	v_mfma_f32_16x16x32_bf16 v[228:231], v[160:163], v[28:31], v[0:3]
	v_exp_f32_e32 v244, v244
	v_exp_f32_e32 v245, v245
	v_mfma_f32_16x16x32_bf16 v[232:235], v[168:171], v[28:31], v[0:3]
	v_exp_f32_e32 v246, v246
	v_add_f32_e32 v154, v244, v245
	v_mfma_f32_16x16x32_bf16 v[228:231], v[164:167], v[32:35], v[228:231]
	v_exp_f32_e32 v247, v247
	v_add_f32_e32 v154, v154, v246
	v_mfma_f32_16x16x32_bf16 v[232:235], v[172:175], v[32:35], v[232:235]
	v_exp_f32_e32 v248, v248
	v_add_f32_e32 v154, v154, v247
	v_mfma_f32_16x16x32_bf16 v[64:67], v[176:179], v[236:239], v[64:67]
	v_exp_f32_e32 v249, v249
	v_add_f32_e32 v154, v154, v248
	v_mfma_f32_16x16x32_bf16 v[60:63], v[180:183], v[236:239], v[60:63]
	v_exp_f32_e32 v250, v250
	v_add_f32_e32 v154, v154, v249
	v_cvt_pk_bf16_f32 v244, v244, v245
	v_mfma_f32_16x16x32_bf16 v[56:59], v[184:187], v[236:239], v[56:59]
	v_exp_f32_e32 v251, v251
	v_add_f32_e32 v154, v154, v250
	v_cvt_pk_bf16_f32 v245, v246, v247
	v_mfma_f32_16x16x32_bf16 v[52:55], v[188:191], v[236:239], v[52:55]
	v_cvt_pk_bf16_f32 v246, v248, v249
	v_cvt_pk_bf16_f32 v247, v250, v251
	v_add_f32_e32 v154, v154, v251
	v_add_f32_e32 v124, v124, v154
	ds_read_b64_tr_b16 v[160:161], v158 offset:20480
	ds_read_b64_tr_b16 v[162:163], v158 offset:22528
	ds_read_b64_tr_b16 v[164:165], v159 offset:20480
	ds_read_b64_tr_b16 v[166:167], v159 offset:22528
	ds_read_b64_tr_b16 v[168:169], v192 offset:20480
	ds_read_b64_tr_b16 v[170:171], v192 offset:22528
	ds_read_b64_tr_b16 v[172:173], v193 offset:20480
	ds_read_b64_tr_b16 v[174:175], v193 offset:22528
	v_mfma_f32_16x16x32_bf16 v[236:239], v[128:131], v[4:7], v[0:3]
	v_exp_f32_e32 v228, v228
	v_exp_f32_e32 v229, v229
	v_mfma_f32_16x16x32_bf16 v[104:107], v[136:139], v[4:7], v[0:3]
	v_exp_f32_e32 v230, v230
	v_add_f32_e32 v154, v228, v229
	v_mfma_f32_16x16x32_bf16 v[236:239], v[132:135], v[8:11], v[236:239]
	v_exp_f32_e32 v231, v231
	v_add_f32_e32 v154, v154, v230
	v_mfma_f32_16x16x32_bf16 v[104:107], v[140:143], v[8:11], v[104:107]
	v_exp_f32_e32 v232, v232
	v_add_f32_e32 v154, v154, v231
	v_mfma_f32_16x16x32_bf16 v[80:83], v[176:179], v[244:247], v[80:83]
	v_exp_f32_e32 v233, v233
	v_add_f32_e32 v154, v154, v232
	v_mfma_f32_16x16x32_bf16 v[76:79], v[180:183], v[244:247], v[76:79]
	v_exp_f32_e32 v234, v234
	v_add_f32_e32 v154, v154, v233
	v_cvt_pk_bf16_f32 v228, v228, v229
	v_mfma_f32_16x16x32_bf16 v[72:75], v[184:187], v[244:247], v[72:75]
	v_exp_f32_e32 v235, v235
	v_add_f32_e32 v154, v154, v234
	v_cvt_pk_bf16_f32 v229, v230, v231
	v_mfma_f32_16x16x32_bf16 v[68:71], v[188:191], v[244:247], v[68:71]
	v_cvt_pk_bf16_f32 v230, v232, v233
	v_cvt_pk_bf16_f32 v231, v234, v235
	v_add_f32_e32 v154, v154, v235
	v_add_f32_e32 v125, v125, v154
	v_mfma_f32_16x16x32_bf16 v[244:247], v[128:131], v[12:15], v[0:3]
	v_exp_f32_e32 v236, v236
	v_exp_f32_e32 v237, v237
	v_mfma_f32_16x16x32_bf16 v[248:251], v[136:139], v[12:15], v[0:3]
	v_exp_f32_e32 v238, v238
	v_add_f32_e32 v154, v236, v237
	v_mfma_f32_16x16x32_bf16 v[244:247], v[132:135], v[16:19], v[244:247]
	v_exp_f32_e32 v239, v239
	v_add_f32_e32 v154, v154, v238
	v_mfma_f32_16x16x32_bf16 v[248:251], v[140:143], v[16:19], v[248:251]
	v_exp_f32_e32 v104, v104
	v_add_f32_e32 v154, v154, v239
	v_mfma_f32_16x16x32_bf16 v[84:87], v[176:179], v[228:231], v[84:87]
	v_exp_f32_e32 v105, v105
	v_add_f32_e32 v154, v154, v104
	v_mfma_f32_16x16x32_bf16 v[92:95], v[180:183], v[228:231], v[92:95]
	v_exp_f32_e32 v106, v106
	v_add_f32_e32 v154, v154, v105
	v_cvt_pk_bf16_f32 v236, v236, v237
	v_mfma_f32_16x16x32_bf16 v[88:91], v[184:187], v[228:231], v[88:91]
	v_exp_f32_e32 v107, v107
	v_add_f32_e32 v154, v154, v106
	v_cvt_pk_bf16_f32 v237, v238, v239
	v_mfma_f32_16x16x32_bf16 v[96:99], v[188:191], v[228:231], v[96:99]
	v_cvt_pk_bf16_f32 v238, v104, v105
	v_cvt_pk_bf16_f32 v239, v106, v107
	v_add_f32_e32 v154, v154, v107
	v_add_f32_e32 v126, v126, v154
	s_waitcnt lgkmcnt(0)
; #define LAS __attribute__((address_space(3)))
; __device__ __forceinline__ s16x4 vtr(const LAS unsigned char* p) { return __builtin_bit_cast(s16x4, __builtin_amdgcn_ds_read_tr16_b64_v4i16((LAS v4i16_t*)p)); }
;     ...
;     for (int gh = 0; gh < 4 / GPB; ++gh) {
;         f32x4 S[GPB][4];
; #pragma unroll
;         for (int kb = 0; kb < 4; ++kb) {
;             const bf16x8 kf0 = *(const LAS bf16x8*)(kb0 + (16 * kb) * 128 + kx0), kf1 = *(const LAS bf16x8*)(kb0 + (16 * kb) * 128 + kx1);
; #pragma unroll
;             for (int gi = 0; gi < GPB; ++gi) { S[gi][kb] = __builtin_amdgcn_mfma_f32_16x16x32_bf16(kf0, qf[GPB * gh + gi][0], cinit, 0, 0, 0);
;                 S[gi][kb] = __builtin_amdgcn_mfma_f32_16x16x32_bf16(kf1, qf[GPB * gh + gi][1], S[gi][kb], 0, 0, 0); } }
;         bf16x8 pf[GPB][2];
; #pragma unroll
;         for (int gi = 0; gi < GPB; ++gi) {
;             if (MASK) {
; #pragma unroll
;                 for (int kb = 0; kb < 4; ++kb)
; #pragma unroll
;                     for (int i = 0; i < 4; ++i) { const int rel = rel0 + 16 * kb + 4 * g + i; S[gi][kb][i] = ((unsigned)(rel + 128) > 256u) ? NEGBIG : S[gi][kb][i]; }
;             }
;             ls[GPB * gh + gi] += exp_step<4>(S[gi]);
;             pf[gi][0] = pack8(S[gi][0], S[gi][1]); pf[gi][1] = pack8(S[gi][2], S[gi][3]);
;         }
; #pragma unroll
;         for (int kc = 0; kc < 2; ++kc)
; #pragma unroll
;             for (int db = 0; db < 4; ++db) {
;                 const LAS unsigned char* va = vrow + ((db ^ swz) << 5) + (32 * kc) * 128;
;                 const bf16x8 vf = cat8(vtr(va), vtr(va + 16 * 128));
; #pragma unroll
;                 for (int gi = 0; gi < GPB; ++gi) O[GPB * gh + gi][db] = __builtin_amdgcn_mfma_f32_16x16x32_bf16(vf, pf[gi][kc], O[GPB * gh + gi][db], 0, 0, 0);
;             }
; __device__ __forceinline__ void na_phase(LAS unsigned char* lds, const bf16_t* Q, const bf16_t* K, const bf16_t* V, bf16_t* Ob, const float* rpb, float negb) {
;     ...
;         for (int t = 0; t < 4; ++t) {
;             dma_tile<2>(lds + ((t + 3) & 3) * NA_BUF, K, V, NA_ROW0(t + 3), DM, dl, w);
;             const LAS unsigned char* buf = lds + (t & 3) * NA_BUF;
;             full_tile<0, 1, 2>(O, ls, qf, negb, buf + hh * 8192, buf + 2 * 8192 + hh * 8192, lane, 0);
;             ring_wait<4>();
	v_mfma_f32_16x16x32_bf16 v[228:231], v[128:131], v[20:23], v[0:3]
	v_exp_f32_e32 v244, v244
	v_exp_f32_e32 v245, v245
	v_mfma_f32_16x16x32_bf16 v[232:235], v[136:139], v[20:23], v[0:3]
	v_exp_f32_e32 v246, v246
	v_add_f32_e32 v154, v244, v245
	v_mfma_f32_16x16x32_bf16 v[228:231], v[132:135], v[24:27], v[228:231]
	v_exp_f32_e32 v247, v247
	v_add_f32_e32 v154, v154, v246
	v_mfma_f32_16x16x32_bf16 v[232:235], v[140:143], v[24:27], v[232:235]
	v_exp_f32_e32 v248, v248
	v_add_f32_e32 v154, v154, v247
	v_mfma_f32_16x16x32_bf16 v[48:51], v[160:163], v[236:239], v[48:51]
	v_exp_f32_e32 v249, v249
	v_add_f32_e32 v154, v154, v248
	v_mfma_f32_16x16x32_bf16 v[44:47], v[164:167], v[236:239], v[44:47]
	v_exp_f32_e32 v250, v250
	v_add_f32_e32 v154, v154, v249
	v_cvt_pk_bf16_f32 v244, v244, v245
	v_mfma_f32_16x16x32_bf16 v[40:43], v[168:171], v[236:239], v[40:43]
	v_exp_f32_e32 v251, v251
	v_add_f32_e32 v154, v154, v250
	v_cvt_pk_bf16_f32 v245, v246, v247
	v_mfma_f32_16x16x32_bf16 v[36:39], v[172:175], v[236:239], v[36:39]
	v_cvt_pk_bf16_f32 v246, v248, v249
	v_cvt_pk_bf16_f32 v247, v250, v251
	v_add_f32_e32 v154, v154, v251
	v_add_f32_e32 v127, v127, v154
	v_mfma_f32_16x16x32_bf16 v[236:239], v[128:131], v[28:31], v[0:3]
	v_exp_f32_e32 v228, v228
	v_exp_f32_e32 v229, v229
	v_mfma_f32_16x16x32_bf16 v[104:107], v[136:139], v[28:31], v[0:3]
	v_exp_f32_e32 v230, v230
	v_add_f32_e32 v154, v228, v229
	v_mfma_f32_16x16x32_bf16 v[236:239], v[132:135], v[32:35], v[236:239]
	v_exp_f32_e32 v231, v231
	v_add_f32_e32 v154, v154, v230
	v_mfma_f32_16x16x32_bf16 v[104:107], v[140:143], v[32:35], v[104:107]
	v_exp_f32_e32 v232, v232
	v_add_f32_e32 v154, v154, v231
	v_mfma_f32_16x16x32_bf16 v[64:67], v[160:163], v[244:247], v[64:67]
	v_exp_f32_e32 v233, v233
	v_add_f32_e32 v154, v154, v232
	v_mfma_f32_16x16x32_bf16 v[60:63], v[164:167], v[244:247], v[60:63]
	v_exp_f32_e32 v234, v234
	v_add_f32_e32 v154, v154, v233
	v_cvt_pk_bf16_f32 v228, v228, v229
	v_mfma_f32_16x16x32_bf16 v[56:59], v[168:171], v[244:247], v[56:59]
	v_exp_f32_e32 v235, v235
	v_add_f32_e32 v154, v154, v234
	v_cvt_pk_bf16_f32 v229, v230, v231
	v_mfma_f32_16x16x32_bf16 v[52:55], v[172:175], v[244:247], v[52:55]
	v_cvt_pk_bf16_f32 v230, v232, v233
	v_cvt_pk_bf16_f32 v231, v234, v235
	v_add_f32_e32 v154, v154, v235
	v_add_f32_e32 v124, v124, v154
	v_mfma_f32_16x16x32_bf16 v[80:83], v[160:163], v[228:231], v[80:83]
	v_exp_f32_e32 v236, v236
	v_exp_f32_e32 v237, v237
	v_exp_f32_e32 v238, v238
	v_add_f32_e32 v154, v236, v237
	v_mfma_f32_16x16x32_bf16 v[76:79], v[164:167], v[228:231], v[76:79]
	v_exp_f32_e32 v239, v239
	v_add_f32_e32 v154, v154, v238
	v_exp_f32_e32 v104, v104
	v_add_f32_e32 v154, v154, v239
	v_mfma_f32_16x16x32_bf16 v[72:75], v[168:171], v[228:231], v[72:75]
	v_exp_f32_e32 v105, v105
	v_add_f32_e32 v154, v154, v104
	v_exp_f32_e32 v106, v106
	v_add_f32_e32 v154, v154, v105
	v_cvt_pk_bf16_f32 v236, v236, v237
	v_mfma_f32_16x16x32_bf16 v[68:71], v[172:175], v[228:231], v[68:71]
	v_exp_f32_e32 v107, v107
	v_add_f32_e32 v154, v154, v106
	v_cvt_pk_bf16_f32 v237, v238, v239
	v_cvt_pk_bf16_f32 v238, v104, v105
	v_cvt_pk_bf16_f32 v239, v106, v107
	v_add_f32_e32 v154, v154, v107
	v_add_f32_e32 v125, v125, v154
	v_mfma_f32_16x16x32_bf16 v[84:87], v[160:163], v[236:239], v[84:87]
	v_mfma_f32_16x16x32_bf16 v[92:95], v[164:167], v[236:239], v[92:95]
	v_mfma_f32_16x16x32_bf16 v[88:91], v[168:171], v[236:239], v[88:91]
	v_mfma_f32_16x16x32_bf16 v[96:99], v[172:175], v[236:239], v[96:99]
	s_add_i32 vcc_lo, vcc_lo, 0x8000
	s_add_u32 s94, s94, 64
	s_addc_u32 s95, s95, 0
	s_add_i32 s96, s96, 1
	s_waitcnt vmcnt(8)
	s_barrier
	s_cmp_lt_i32 s96, s93
	s_cselect_b32 s7, s95, 0
	s_cselect_b32 s6, s94, s82
	s_lshl_b64 s[6:7], s[6:7], 11
	s_add_u32 s76, s67, s6
	s_addc_u32 s77, s4, s7
	s_add_u32 s6, s5, s6
	s_addc_u32 s7, s58, s7
	s_add_i32 s59, s69, vcc_lo
	s_mov_b32 vcc_hi, m0
	s_mov_b32 m0, s59
	s_nop 0
	global_load_lds_dwordx4 v221, s[76:77]
	s_mov_b32 m0, vcc_hi
	s_add_i32 s66, s59, 0x4000
	s_mov_b32 vcc_hi, m0
	s_mov_b32 m0, s66
	s_nop 0
	global_load_lds_dwordx4 v222, s[6:7]
	s_mov_b32 m0, vcc_hi
	s_add_i32 s66, s59, 0x2000
	s_mov_b32 vcc_hi, m0
	s_mov_b32 m0, s66
	s_nop 0
	global_load_lds_dwordx4 v223, s[76:77]
	s_mov_b32 m0, vcc_hi
	s_addk_i32 s59, 0x6000
	s_mov_b32 s66, m0
	s_mov_b32 m0, s59
	s_nop 0
	global_load_lds_dwordx4 v224, s[6:7]
	s_mov_b32 m0, s66
	s_add_i32 s76, s65, vcc_lo
	s_add_i32 s76, s76, 0x8000
	v_add_u32_e32 v144, s76, v111
	v_add3_u32 v193, s76, v210, v205
	v_add_u32_e32 v145, v144, v204
	v_add_u32_e32 v144, v144, v203
	ds_read_b128 v[160:163], v144
	ds_read_b128 v[164:167], v145
	ds_read_b128 v[168:171], v144 offset:2048
	ds_read_b128 v[172:175], v145 offset:2048
	ds_read_b128 v[128:131], v144 offset:4096
	ds_read_b128 v[132:135], v145 offset:4096
	ds_read_b128 v[136:139], v144 offset:6144
	ds_read_b128 v[140:143], v145 offset:6144
	v_add_u32_e32 v158, v193, v206
	v_add_u32_e32 v159, v193, v207
	v_add_u32_e32 v192, v193, v208
	v_add_u32_e32 v193, v193, v209
	s_waitcnt lgkmcnt(4)
; #define LAS __attribute__((address_space(3)))
; __device__ __forceinline__ s16x4 vtr(const LAS unsigned char* p) { return __builtin_bit_cast(s16x4, __builtin_amdgcn_ds_read_tr16_b64_v4i16((LAS v4i16_t*)p)); }
; __device__ __forceinline__ bf16x8 cat8(s16x4 a, s16x4 b) { return (bf16x8){a[0], a[1], a[2], a[3], b[0], b[1], b[2], b[3]}; }
; __device__ __forceinline__ bf16x8 pack8(const f32x4& a, const f32x4& b) { u32x4 w; w.x = pkbf(a[0], a[1]); w.y = pkbf(a[2], a[3]); w.z = pkbf(b[0], b[1]); w.w = pkbf(b[2], b[3]); return __builtin_bit_cast(bf16x8, w); }
;     ...
;     for (int gh = 0; gh < 4 / GPB; ++gh) {
;         f32x4 S[GPB][4];
; #pragma unroll
;         for (int kb = 0; kb < 4; ++kb) {
;             const bf16x8 kf0 = *(const LAS bf16x8*)(kb0 + (16 * kb) * 128 + kx0), kf1 = *(const LAS bf16x8*)(kb0 + (16 * kb) * 128 + kx1);
; #pragma unroll
;             for (int gi = 0; gi < GPB; ++gi) { S[gi][kb] = __builtin_amdgcn_mfma_f32_16x16x32_bf16(kf0, qf[GPB * gh + gi][0], cinit, 0, 0, 0);
;                 S[gi][kb] = __builtin_amdgcn_mfma_f32_16x16x32_bf16(kf1, qf[GPB * gh + gi][1], S[gi][kb], 0, 0, 0); } }
;         bf16x8 pf[GPB][2];
; #pragma unroll
;         for (int gi = 0; gi < GPB; ++gi) {
;             if (MASK) {
; #pragma unroll
;                 for (int kb = 0; kb < 4; ++kb)
; #pragma unroll
;                     for (int i = 0; i < 4; ++i) { const int rel = rel0 + 16 * kb + 4 * g + i; S[gi][kb][i] = ((unsigned)(rel + 128) > 256u) ? NEGBIG : S[gi][kb][i]; }
;             }
;             ls[GPB * gh + gi] += exp_step<4>(S[gi]);
;             pf[gi][0] = pack8(S[gi][0], S[gi][1]); pf[gi][1] = pack8(S[gi][2], S[gi][3]);
;         }
; #pragma unroll
;         for (int kc = 0; kc < 2; ++kc)
; #pragma unroll
;             for (int db = 0; db < 4; ++db) {
;                 const LAS unsigned char* va = vrow + ((db ^ swz) << 5) + (32 * kc) * 128;
;                 const bf16x8 vf = cat8(vtr(va), vtr(va + 16 * 128));
; #pragma unroll
;                 for (int gi = 0; gi < GPB; ++gi) O[GPB * gh + gi][db] = __builtin_amdgcn_mfma_f32_16x16x32_bf16(vf, pf[gi][kc], O[GPB * gh + gi][db], 0, 0, 0);
;             }
	v_mfma_f32_16x16x32_bf16 v[228:231], v[160:163], v[4:7], v[0:3]
	v_mfma_f32_16x16x32_bf16 v[232:235], v[168:171], v[4:7], v[0:3]
	v_mfma_f32_16x16x32_bf16 v[228:231], v[164:167], v[8:11], v[228:231]
	v_mfma_f32_16x16x32_bf16 v[232:235], v[172:175], v[8:11], v[232:235]
	ds_read_b64_tr_b16 v[176:177], v158 offset:16384
	ds_read_b64_tr_b16 v[178:179], v158 offset:18432
	ds_read_b64_tr_b16 v[180:181], v159 offset:16384
	ds_read_b64_tr_b16 v[182:183], v159 offset:18432
	ds_read_b64_tr_b16 v[184:185], v192 offset:16384
	ds_read_b64_tr_b16 v[186:187], v192 offset:18432
	ds_read_b64_tr_b16 v[188:189], v193 offset:16384
	ds_read_b64_tr_b16 v[190:191], v193 offset:18432
	v_mfma_f32_16x16x32_bf16 v[236:239], v[160:163], v[12:15], v[0:3]
	v_exp_f32_e32 v228, v228
	v_exp_f32_e32 v229, v229
	v_exp_f32_e32 v230, v230
	v_add_f32_e32 v154, v228, v229
	v_mfma_f32_16x16x32_bf16 v[104:107], v[168:171], v[12:15], v[0:3]
	v_exp_f32_e32 v231, v231
	v_add_f32_e32 v154, v154, v230
	v_exp_f32_e32 v232, v232
	v_add_f32_e32 v154, v154, v231
	v_mfma_f32_16x16x32_bf16 v[236:239], v[164:167], v[16:19], v[236:239]
	v_exp_f32_e32 v233, v233
	v_add_f32_e32 v154, v154, v232
	v_exp_f32_e32 v234, v234
	v_add_f32_e32 v154, v154, v233
	v_cvt_pk_bf16_f32 v228, v228, v229
	v_mfma_f32_16x16x32_bf16 v[104:107], v[172:175], v[16:19], v[104:107]
	v_exp_f32_e32 v235, v235
	v_add_f32_e32 v154, v154, v234
	v_cvt_pk_bf16_f32 v229, v230, v231
	v_cvt_pk_bf16_f32 v230, v232, v233
	v_cvt_pk_bf16_f32 v231, v234, v235
	v_add_f32_e32 v154, v154, v235
	v_add_f32_e32 v126, v126, v154
	s_waitcnt lgkmcnt(0)
	v_mfma_f32_16x16x32_bf16 v[244:247], v[160:163], v[20:23], v[0:3]
	v_exp_f32_e32 v236, v236
	v_exp_f32_e32 v237, v237
	v_mfma_f32_16x16x32_bf16 v[248:251], v[168:171], v[20:23], v[0:3]
	v_exp_f32_e32 v238, v238
	v_add_f32_e32 v154, v236, v237
	v_mfma_f32_16x16x32_bf16 v[244:247], v[164:167], v[24:27], v[244:247]
	v_exp_f32_e32 v239, v239
	v_add_f32_e32 v154, v154, v238
	v_mfma_f32_16x16x32_bf16 v[248:251], v[172:175], v[24:27], v[248:251]
	v_exp_f32_e32 v104, v104
	v_add_f32_e32 v154, v154, v239
	v_mfma_f32_16x16x32_bf16 v[48:51], v[176:179], v[228:231], v[48:51]
	v_exp_f32_e32 v105, v105
	v_add_f32_e32 v154, v154, v104
	v_mfma_f32_16x16x32_bf16 v[44:47], v[180:183], v[228:231], v[44:47]
	v_exp_f32_e32 v106, v106
	v_add_f32_e32 v154, v154, v105
	v_cvt_pk_bf16_f32 v236, v236, v237
	v_mfma_f32_16x16x32_bf16 v[40:43], v[184:187], v[228:231], v[40:43]
	v_exp_f32_e32 v107, v107
	v_add_f32_e32 v154, v154, v106
	v_cvt_pk_bf16_f32 v237, v238, v239
	v_mfma_f32_16x16x32_bf16 v[36:39], v[188:191], v[228:231], v[36:39]
	v_cvt_pk_bf16_f32 v238, v104, v105
	v_cvt_pk_bf16_f32 v239, v106, v107
	v_add_f32_e32 v154, v154, v107
	v_add_f32_e32 v127, v127, v154
	v_mfma_f32_16x16x32_bf16 v[228:231], v[160:163], v[28:31], v[0:3]
	v_exp_f32_e32 v244, v244
	v_exp_f32_e32 v245, v245
	v_mfma_f32_16x16x32_bf16 v[232:235], v[168:171], v[28:31], v[0:3]
	v_exp_f32_e32 v246, v246
	v_add_f32_e32 v154, v244, v245
	v_mfma_f32_16x16x32_bf16 v[228:231], v[164:167], v[32:35], v[228:231]
	v_exp_f32_e32 v247, v247
	v_add_f32_e32 v154, v154, v246
	v_mfma_f32_16x16x32_bf16 v[232:235], v[172:175], v[32:35], v[232:235]
	v_exp_f32_e32 v248, v248
	v_add_f32_e32 v154, v154, v247
	v_mfma_f32_16x16x32_bf16 v[64:67], v[176:179], v[236:239], v[64:67]
	v_exp_f32_e32 v249, v249
	v_add_f32_e32 v154, v154, v248
	v_mfma_f32_16x16x32_bf16 v[60:63], v[180:183], v[236:239], v[60:63]
	v_exp_f32_e32 v250, v250
	v_add_f32_e32 v154, v154, v249
	v_cvt_pk_bf16_f32 v244, v244, v245
	v_mfma_f32_16x16x32_bf16 v[56:59], v[184:187], v[236:239], v[56:59]
	v_exp_f32_e32 v251, v251
	v_add_f32_e32 v154, v154, v250
	v_cvt_pk_bf16_f32 v245, v246, v247
	v_mfma_f32_16x16x32_bf16 v[52:55], v[188:191], v[236:239], v[52:55]
	v_cvt_pk_bf16_f32 v246, v248, v249
	v_cvt_pk_bf16_f32 v247, v250, v251
	v_add_f32_e32 v154, v154, v251
	v_add_f32_e32 v124, v124, v154
	ds_read_b64_tr_b16 v[160:161], v158 offset:20480
	ds_read_b64_tr_b16 v[162:163], v158 offset:22528
	ds_read_b64_tr_b16 v[164:165], v159 offset:20480
	ds_read_b64_tr_b16 v[166:167], v159 offset:22528
	ds_read_b64_tr_b16 v[168:169], v192 offset:20480
	ds_read_b64_tr_b16 v[170:171], v192 offset:22528
	ds_read_b64_tr_b16 v[172:173], v193 offset:20480
	ds_read_b64_tr_b16 v[174:175], v193 offset:22528
	v_mfma_f32_16x16x32_bf16 v[236:239], v[128:131], v[4:7], v[0:3]
	v_exp_f32_e32 v228, v228
	v_exp_f32_e32 v229, v229
	v_mfma_f32_16x16x32_bf16 v[104:107], v[136:139], v[4:7], v[0:3]
	v_exp_f32_e32 v230, v230
	v_add_f32_e32 v154, v228, v229
	v_mfma_f32_16x16x32_bf16 v[236:239], v[132:135], v[8:11], v[236:239]
	v_exp_f32_e32 v231, v231
	v_add_f32_e32 v154, v154, v230
	v_mfma_f32_16x16x32_bf16 v[104:107], v[140:143], v[8:11], v[104:107]
	v_exp_f32_e32 v232, v232
	v_add_f32_e32 v154, v154, v231
	v_mfma_f32_16x16x32_bf16 v[80:83], v[176:179], v[244:247], v[80:83]
	v_exp_f32_e32 v233, v233
	v_add_f32_e32 v154, v154, v232
	v_mfma_f32_16x16x32_bf16 v[76:79], v[180:183], v[244:247], v[76:79]
	v_exp_f32_e32 v234, v234
	v_add_f32_e32 v154, v154, v233
	v_cvt_pk_bf16_f32 v228, v228, v229
	v_mfma_f32_16x16x32_bf16 v[72:75], v[184:187], v[244:247], v[72:75]
	v_exp_f32_e32 v235, v235
	v_add_f32_e32 v154, v154, v234
	v_cvt_pk_bf16_f32 v229, v230, v231
	v_mfma_f32_16x16x32_bf16 v[68:71], v[188:191], v[244:247], v[68:71]
	v_cvt_pk_bf16_f32 v230, v232, v233
	v_cvt_pk_bf16_f32 v231, v234, v235
	v_add_f32_e32 v154, v154, v235
	v_add_f32_e32 v125, v125, v154
	v_mfma_f32_16x16x32_bf16 v[244:247], v[128:131], v[12:15], v[0:3]
	v_exp_f32_e32 v236, v236
	v_exp_f32_e32 v237, v237
	v_mfma_f32_16x16x32_bf16 v[248:251], v[136:139], v[12:15], v[0:3]
	v_exp_f32_e32 v238, v238
	v_add_f32_e32 v154, v236, v237
	v_mfma_f32_16x16x32_bf16 v[244:247], v[132:135], v[16:19], v[244:247]
	v_exp_f32_e32 v239, v239
	v_add_f32_e32 v154, v154, v238
	v_mfma_f32_16x16x32_bf16 v[248:251], v[140:143], v[16:19], v[248:251]
	v_exp_f32_e32 v104, v104
	v_add_f32_e32 v154, v154, v239
	v_mfma_f32_16x16x32_bf16 v[84:87], v[176:179], v[228:231], v[84:87]
	v_exp_f32_e32 v105, v105
	v_add_f32_e32 v154, v154, v104
	v_mfma_f32_16x16x32_bf16 v[92:95], v[180:183], v[228:231], v[92:95]
	v_exp_f32_e32 v106, v106
	v_add_f32_e32 v154, v154, v105
	v_cvt_pk_bf16_f32 v236, v236, v237
	v_mfma_f32_16x16x32_bf16 v[88:91], v[184:187], v[228:231], v[88:91]
	v_exp_f32_e32 v107, v107
	v_add_f32_e32 v154, v154, v106
	v_cvt_pk_bf16_f32 v237, v238, v239
	v_mfma_f32_16x16x32_bf16 v[96:99], v[188:191], v[228:231], v[96:99]
	v_cvt_pk_bf16_f32 v238, v104, v105
	v_cvt_pk_bf16_f32 v239, v106, v107
	v_add_f32_e32 v154, v154, v107
	v_add_f32_e32 v126, v126, v154
	s_waitcnt lgkmcnt(0)
; #define LAS __attribute__((address_space(3)))
; __device__ __forceinline__ s16x4 vtr(const LAS unsigned char* p) { return __builtin_bit_cast(s16x4, __builtin_amdgcn_ds_read_tr16_b64_v4i16((LAS v4i16_t*)p)); }
; __device__ __forceinline__ bf16x8 cat8(s16x4 a, s16x4 b) { return (bf16x8){a[0], a[1], a[2], a[3], b[0], b[1], b[2], b[3]}; }
; __device__ __forceinline__ bf16x8 pack8(const f32x4& a, const f32x4& b) { u32x4 w; w.x = pkbf(a[0], a[1]); w.y = pkbf(a[2], a[3]); w.z = pkbf(b[0], b[1]); w.w = pkbf(b[2], b[3]); return __builtin_bit_cast(bf16x8, w); }
; template <int NI> __device__ __forceinline__ void ring_wait() { asm volatile("s_waitcnt vmcnt(%0)" :: "n"(2 * NI) : "memory"); __syncthreads(); }
; template <int NB16> __device__ __forceinline__ float exp_step(f32x4 (&S)[NB16]) {
;     float sum = 0.f;
; #pragma unroll
;     for (int k = 0; k < NB16; ++k)
; #pragma unroll
;         for (int i = 0; i < 4; ++i) { S[k][i] = __builtin_amdgcn_exp2f(S[k][i]); sum += S[k][i]; }
;     return sum;
;     ...
;             ls[GPB * gh + gi] += exp_step<4>(S[gi]);
;             pf[gi][0] = pack8(S[gi][0], S[gi][1]); pf[gi][1] = pack8(S[gi][2], S[gi][3]);
;         }
; #pragma unroll
;         for (int kc = 0; kc < 2; ++kc)
; #pragma unroll
;             for (int db = 0; db < 4; ++db) {
;                 const LAS unsigned char* va = vrow + ((db ^ swz) << 5) + (32 * kc) * 128;
;                 const bf16x8 vf = cat8(vtr(va), vtr(va + 16 * 128));
; #pragma unroll
;                 for (int gi = 0; gi < GPB; ++gi) O[GPB * gh + gi][db] = __builtin_amdgcn_mfma_f32_16x16x32_bf16(vf, pf[gi][kc], O[GPB * gh + gi][db], 0, 0, 0);
; __device__ __forceinline__ void na_phase(LAS unsigned char* lds, const bf16_t* Q, const bf16_t* K, const bf16_t* V, bf16_t* Ob, const float* rpb, float negb) {
;     ...
;         for (int t = 0; t < 4; ++t) {
;             dma_tile<2>(lds + ((t + 3) & 3) * NA_BUF, K, V, NA_ROW0(t + 3), DM, dl, w);
;             const LAS unsigned char* buf = lds + (t & 3) * NA_BUF;
;             full_tile<0, 1, 2>(O, ls, qf, negb, buf + hh * 8192, buf + 2 * 8192 + hh * 8192, lane, 0);
;             ring_wait<4>();
;         }
	v_mfma_f32_16x16x32_bf16 v[228:231], v[128:131], v[20:23], v[0:3]
	v_exp_f32_e32 v244, v244
	v_exp_f32_e32 v245, v245
	v_mfma_f32_16x16x32_bf16 v[232:235], v[136:139], v[20:23], v[0:3]
	v_exp_f32_e32 v246, v246
	v_add_f32_e32 v154, v244, v245
	v_mfma_f32_16x16x32_bf16 v[228:231], v[132:135], v[24:27], v[228:231]
	v_exp_f32_e32 v247, v247
	v_add_f32_e32 v154, v154, v246
	v_mfma_f32_16x16x32_bf16 v[232:235], v[140:143], v[24:27], v[232:235]
	v_exp_f32_e32 v248, v248
	v_add_f32_e32 v154, v154, v247
	v_mfma_f32_16x16x32_bf16 v[48:51], v[160:163], v[236:239], v[48:51]
	v_exp_f32_e32 v249, v249
	v_add_f32_e32 v154, v154, v248
	v_mfma_f32_16x16x32_bf16 v[44:47], v[164:167], v[236:239], v[44:47]
	v_exp_f32_e32 v250, v250
	v_add_f32_e32 v154, v154, v249
	v_cvt_pk_bf16_f32 v244, v244, v245
	v_mfma_f32_16x16x32_bf16 v[40:43], v[168:171], v[236:239], v[40:43]
	v_exp_f32_e32 v251, v251
	v_add_f32_e32 v154, v154, v250
	v_cvt_pk_bf16_f32 v245, v246, v247
	v_mfma_f32_16x16x32_bf16 v[36:39], v[172:175], v[236:239], v[36:39]
	v_cvt_pk_bf16_f32 v246, v248, v249
	v_cvt_pk_bf16_f32 v247, v250, v251
	v_add_f32_e32 v154, v154, v251
	v_add_f32_e32 v127, v127, v154
	v_mfma_f32_16x16x32_bf16 v[236:239], v[128:131], v[28:31], v[0:3]
	v_exp_f32_e32 v228, v228
	v_exp_f32_e32 v229, v229
	v_mfma_f32_16x16x32_bf16 v[104:107], v[136:139], v[28:31], v[0:3]
	v_exp_f32_e32 v230, v230
	v_add_f32_e32 v154, v228, v229
	v_mfma_f32_16x16x32_bf16 v[236:239], v[132:135], v[32:35], v[236:239]
	v_exp_f32_e32 v231, v231
	v_add_f32_e32 v154, v154, v230
	v_mfma_f32_16x16x32_bf16 v[104:107], v[140:143], v[32:35], v[104:107]
	v_exp_f32_e32 v232, v232
	v_add_f32_e32 v154, v154, v231
	v_mfma_f32_16x16x32_bf16 v[64:67], v[160:163], v[244:247], v[64:67]
	v_exp_f32_e32 v233, v233
	v_add_f32_e32 v154, v154, v232
	v_mfma_f32_16x16x32_bf16 v[60:63], v[164:167], v[244:247], v[60:63]
	v_exp_f32_e32 v234, v234
	v_add_f32_e32 v154, v154, v233
	v_cvt_pk_bf16_f32 v228, v228, v229
	v_mfma_f32_16x16x32_bf16 v[56:59], v[168:171], v[244:247], v[56:59]
	v_exp_f32_e32 v235, v235
	v_add_f32_e32 v154, v154, v234
	v_cvt_pk_bf16_f32 v229, v230, v231
	v_mfma_f32_16x16x32_bf16 v[52:55], v[172:175], v[244:247], v[52:55]
	v_cvt_pk_bf16_f32 v230, v232, v233
	v_cvt_pk_bf16_f32 v231, v234, v235
	v_add_f32_e32 v154, v154, v235
	v_add_f32_e32 v124, v124, v154
	v_mfma_f32_16x16x32_bf16 v[80:83], v[160:163], v[228:231], v[80:83]
	v_exp_f32_e32 v236, v236
	v_exp_f32_e32 v237, v237
	v_exp_f32_e32 v238, v238
	v_add_f32_e32 v154, v236, v237
	v_mfma_f32_16x16x32_bf16 v[76:79], v[164:167], v[228:231], v[76:79]
	v_exp_f32_e32 v239, v239
	v_add_f32_e32 v154, v154, v238
	v_exp_f32_e32 v104, v104
	v_add_f32_e32 v154, v154, v239
	v_mfma_f32_16x16x32_bf16 v[72:75], v[168:171], v[228:231], v[72:75]
	v_exp_f32_e32 v105, v105
	v_add_f32_e32 v154, v154, v104
	v_exp_f32_e32 v106, v106
	v_add_f32_e32 v154, v154, v105
	v_cvt_pk_bf16_f32 v236, v236, v237
	v_mfma_f32_16x16x32_bf16 v[68:71], v[172:175], v[228:231], v[68:71]
	v_exp_f32_e32 v107, v107
	v_add_f32_e32 v154, v154, v106
	v_cvt_pk_bf16_f32 v237, v238, v239
	v_cvt_pk_bf16_f32 v238, v104, v105
	v_cvt_pk_bf16_f32 v239, v106, v107
	v_add_f32_e32 v154, v154, v107
	v_add_f32_e32 v125, v125, v154
	v_mfma_f32_16x16x32_bf16 v[84:87], v[160:163], v[236:239], v[84:87]
	v_mfma_f32_16x16x32_bf16 v[92:95], v[164:167], v[236:239], v[92:95]
	v_mfma_f32_16x16x32_bf16 v[88:91], v[168:171], v[236:239], v[88:91]
	v_mfma_f32_16x16x32_bf16 v[96:99], v[172:175], v[236:239], v[96:99]
	s_add_i32 vcc_lo, vcc_lo, 0x8000
	s_add_u32 s94, s94, 64
	s_addc_u32 s95, s95, 0
	s_add_i32 s96, s96, 1
	s_waitcnt vmcnt(8)
	s_barrier
	s_cmp_lt_i32 s96, s93
	s_cselect_b32 s7, s95, 0
	s_cselect_b32 s6, s94, s82
	s_lshl_b64 s[6:7], s[6:7], 11
	s_add_u32 s76, s67, s6
	s_addc_u32 s77, s4, s7
	s_add_u32 s6, s5, s6
	s_addc_u32 s7, s58, s7
	s_add_i32 s59, s69, vcc_lo
	s_mov_b32 vcc_hi, m0
	s_mov_b32 m0, s59
	s_nop 0
	global_load_lds_dwordx4 v221, s[76:77]
	s_mov_b32 m0, vcc_hi
	s_add_i32 s66, s59, 0x4000
	s_mov_b32 vcc_hi, m0
	s_mov_b32 m0, s66
	s_nop 0
	global_load_lds_dwordx4 v222, s[6:7]
	s_mov_b32 m0, vcc_hi
	s_add_i32 s66, s59, 0x2000
	s_mov_b32 vcc_hi, m0
	s_mov_b32 m0, s66
	s_nop 0
	global_load_lds_dwordx4 v223, s[76:77]
	s_mov_b32 m0, vcc_hi
	s_addk_i32 s59, 0x6000
	s_mov_b32 s66, m0
	s_mov_b32 m0, s59
	s_nop 0
	global_load_lds_dwordx4 v224, s[6:7]
	s_mov_b32 m0, s66
	s_add_i32 s76, s65, vcc_lo
	s_add_i32 s76, s76, 0x8000
	v_add_u32_e32 v144, s76, v111
	v_add3_u32 v193, s76, v210, v205
	v_add_u32_e32 v145, v144, v204
	v_add_u32_e32 v144, v144, v203
	ds_read_b128 v[160:163], v144
	ds_read_b128 v[164:167], v145
	ds_read_b128 v[168:171], v144 offset:2048
	ds_read_b128 v[172:175], v145 offset:2048
	ds_read_b128 v[128:131], v144 offset:4096
	ds_read_b128 v[132:135], v145 offset:4096
	ds_read_b128 v[136:139], v144 offset:6144
	ds_read_b128 v[140:143], v145 offset:6144
	v_add_u32_e32 v158, v193, v206
	v_add_u32_e32 v159, v193, v207
	v_add_u32_e32 v192, v193, v208
	v_add_u32_e32 v193, v193, v209
	s_waitcnt lgkmcnt(4)
; #define LAS __attribute__((address_space(3)))
; __device__ __forceinline__ s16x4 vtr(const LAS unsigned char* p) { return __builtin_bit_cast(s16x4, __builtin_amdgcn_ds_read_tr16_b64_v4i16((LAS v4i16_t*)p)); }
; __device__ __forceinline__ bf16x8 cat8(s16x4 a, s16x4 b) { return (bf16x8){a[0], a[1], a[2], a[3], b[0], b[1], b[2], b[3]}; }
; __device__ __forceinline__ bf16x8 pack8(const f32x4& a, const f32x4& b) { u32x4 w; w.x = pkbf(a[0], a[1]); w.y = pkbf(a[2], a[3]); w.z = pkbf(b[0], b[1]); w.w = pkbf(b[2], b[3]); return __builtin_bit_cast(bf16x8, w); }
;     ...
;     for (int gh = 0; gh < 4 / GPB; ++gh) {
;         f32x4 S[GPB][4];
; #pragma unroll
;         for (int kb = 0; kb < 4; ++kb) {
;             const bf16x8 kf0 = *(const LAS bf16x8*)(kb0 + (16 * kb) * 128 + kx0), kf1 = *(const LAS bf16x8*)(kb0 + (16 * kb) * 128 + kx1);
; #pragma unroll
;             for (int gi = 0; gi < GPB; ++gi) { S[gi][kb] = __builtin_amdgcn_mfma_f32_16x16x32_bf16(kf0, qf[GPB * gh + gi][0], cinit, 0, 0, 0);
;                 S[gi][kb] = __builtin_amdgcn_mfma_f32_16x16x32_bf16(kf1, qf[GPB * gh + gi][1], S[gi][kb], 0, 0, 0); } }
;         bf16x8 pf[GPB][2];
; #pragma unroll
;         for (int gi = 0; gi < GPB; ++gi) {
;             if (MASK) {
; #pragma unroll
;                 for (int kb = 0; kb < 4; ++kb)
; #pragma unroll
;                     for (int i = 0; i < 4; ++i) { const int rel = rel0 + 16 * kb + 4 * g + i; S[gi][kb][i] = ((unsigned)(rel + 128) > 256u) ? NEGBIG : S[gi][kb][i]; }
;             }
;             ls[GPB * gh + gi] += exp_step<4>(S[gi]);
;             pf[gi][0] = pack8(S[gi][0], S[gi][1]); pf[gi][1] = pack8(S[gi][2], S[gi][3]);
;         }
; #pragma unroll
;         for (int kc = 0; kc < 2; ++kc)
; #pragma unroll
;             for (int db = 0; db < 4; ++db) {
;                 const LAS unsigned char* va = vrow + ((db ^ swz) << 5) + (32 * kc) * 128;
;                 const bf16x8 vf = cat8(vtr(va), vtr(va + 16 * 128));
; #pragma unroll
;                 for (int gi = 0; gi < GPB; ++gi) O[GPB * gh + gi][db] = __builtin_amdgcn_mfma_f32_16x16x32_bf16(vf, pf[gi][kc], O[GPB * gh + gi][db], 0, 0, 0);
;             }
;         if (SB == 1) __builtin_amdgcn_sched_barrier(0); else if (SB == 2) __builtin_amdgcn_sched_barrier(0x108);
;     }
	v_mfma_f32_16x16x32_bf16 v[228:231], v[160:163], v[4:7], v[0:3]
	v_mfma_f32_16x16x32_bf16 v[232:235], v[168:171], v[4:7], v[0:3]
	v_mfma_f32_16x16x32_bf16 v[228:231], v[164:167], v[8:11], v[228:231]
	v_mfma_f32_16x16x32_bf16 v[232:235], v[172:175], v[8:11], v[232:235]
	ds_read_b64_tr_b16 v[176:177], v158 offset:16384
	ds_read_b64_tr_b16 v[178:179], v158 offset:18432
	ds_read_b64_tr_b16 v[180:181], v159 offset:16384
	ds_read_b64_tr_b16 v[182:183], v159 offset:18432
	ds_read_b64_tr_b16 v[184:185], v192 offset:16384
	ds_read_b64_tr_b16 v[186:187], v192 offset:18432
	ds_read_b64_tr_b16 v[188:189], v193 offset:16384
	ds_read_b64_tr_b16 v[190:191], v193 offset:18432
	v_mfma_f32_16x16x32_bf16 v[236:239], v[160:163], v[12:15], v[0:3]
	v_exp_f32_e32 v228, v228
	v_exp_f32_e32 v229, v229
	v_exp_f32_e32 v230, v230
	v_add_f32_e32 v154, v228, v229
	v_mfma_f32_16x16x32_bf16 v[104:107], v[168:171], v[12:15], v[0:3]
	v_exp_f32_e32 v231, v231
	v_add_f32_e32 v154, v154, v230
	v_exp_f32_e32 v232, v232
	v_add_f32_e32 v154, v154, v231
	v_mfma_f32_16x16x32_bf16 v[236:239], v[164:167], v[16:19], v[236:239]
	v_exp_f32_e32 v233, v233
	v_add_f32_e32 v154, v154, v232
	v_exp_f32_e32 v234, v234
	v_add_f32_e32 v154, v154, v233
	v_cvt_pk_bf16_f32 v228, v228, v229
	v_mfma_f32_16x16x32_bf16 v[104:107], v[172:175], v[16:19], v[104:107]
	v_exp_f32_e32 v235, v235
	v_add_f32_e32 v154, v154, v234
	v_cvt_pk_bf16_f32 v229, v230, v231
	v_cvt_pk_bf16_f32 v230, v232, v233
	v_cvt_pk_bf16_f32 v231, v234, v235
	v_add_f32_e32 v154, v154, v235
	v_add_f32_e32 v126, v126, v154
	s_waitcnt lgkmcnt(0)
	v_mfma_f32_16x16x32_bf16 v[244:247], v[160:163], v[20:23], v[0:3]
	v_exp_f32_e32 v236, v236
	v_exp_f32_e32 v237, v237
	v_mfma_f32_16x16x32_bf16 v[248:251], v[168:171], v[20:23], v[0:3]
	v_exp_f32_e32 v238, v238
	v_add_f32_e32 v154, v236, v237
	v_mfma_f32_16x16x32_bf16 v[244:247], v[164:167], v[24:27], v[244:247]
	v_exp_f32_e32 v239, v239
	v_add_f32_e32 v154, v154, v238
	v_mfma_f32_16x16x32_bf16 v[248:251], v[172:175], v[24:27], v[248:251]
	v_exp_f32_e32 v104, v104
	v_add_f32_e32 v154, v154, v239
	v_mfma_f32_16x16x32_bf16 v[48:51], v[176:179], v[228:231], v[48:51]
	v_exp_f32_e32 v105, v105
	v_add_f32_e32 v154, v154, v104
	v_mfma_f32_16x16x32_bf16 v[44:47], v[180:183], v[228:231], v[44:47]
	v_exp_f32_e32 v106, v106
	v_add_f32_e32 v154, v154, v105
	v_cvt_pk_bf16_f32 v236, v236, v237
	v_mfma_f32_16x16x32_bf16 v[40:43], v[184:187], v[228:231], v[40:43]
	v_exp_f32_e32 v107, v107
	v_add_f32_e32 v154, v154, v106
	v_cvt_pk_bf16_f32 v237, v238, v239
	v_mfma_f32_16x16x32_bf16 v[36:39], v[188:191], v[228:231], v[36:39]
	v_cvt_pk_bf16_f32 v238, v104, v105
	v_cvt_pk_bf16_f32 v239, v106, v107
	v_add_f32_e32 v154, v154, v107
	v_add_f32_e32 v127, v127, v154
	v_mfma_f32_16x16x32_bf16 v[228:231], v[160:163], v[28:31], v[0:3]
	v_exp_f32_e32 v244, v244
	v_exp_f32_e32 v245, v245
	v_mfma_f32_16x16x32_bf16 v[232:235], v[168:171], v[28:31], v[0:3]
	v_exp_f32_e32 v246, v246
	v_add_f32_e32 v154, v244, v245
	v_mfma_f32_16x16x32_bf16 v[228:231], v[164:167], v[32:35], v[228:231]
	v_exp_f32_e32 v247, v247
	v_add_f32_e32 v154, v154, v246
	v_mfma_f32_16x16x32_bf16 v[232:235], v[172:175], v[32:35], v[232:235]
	v_exp_f32_e32 v248, v248
	v_add_f32_e32 v154, v154, v247
	v_mfma_f32_16x16x32_bf16 v[64:67], v[176:179], v[236:239], v[64:67]
	v_exp_f32_e32 v249, v249
	v_add_f32_e32 v154, v154, v248
	v_mfma_f32_16x16x32_bf16 v[60:63], v[180:183], v[236:239], v[60:63]
	v_exp_f32_e32 v250, v250
	v_add_f32_e32 v154, v154, v249
	v_cvt_pk_bf16_f32 v244, v244, v245
	v_mfma_f32_16x16x32_bf16 v[56:59], v[184:187], v[236:239], v[56:59]
	v_exp_f32_e32 v251, v251
	v_add_f32_e32 v154, v154, v250
	v_cvt_pk_bf16_f32 v245, v246, v247
	v_mfma_f32_16x16x32_bf16 v[52:55], v[188:191], v[236:239], v[52:55]
	v_cvt_pk_bf16_f32 v246, v248, v249
	v_cvt_pk_bf16_f32 v247, v250, v251
	v_add_f32_e32 v154, v154, v251
	v_add_f32_e32 v124, v124, v154
	ds_read_b64_tr_b16 v[160:161], v158 offset:20480
	ds_read_b64_tr_b16 v[162:163], v158 offset:22528
	ds_read_b64_tr_b16 v[164:165], v159 offset:20480
	ds_read_b64_tr_b16 v[166:167], v159 offset:22528
	ds_read_b64_tr_b16 v[168:169], v192 offset:20480
	ds_read_b64_tr_b16 v[170:171], v192 offset:22528
	ds_read_b64_tr_b16 v[172:173], v193 offset:20480
	ds_read_b64_tr_b16 v[174:175], v193 offset:22528
	v_mfma_f32_16x16x32_bf16 v[236:239], v[128:131], v[4:7], v[0:3]
	v_exp_f32_e32 v228, v228
	v_exp_f32_e32 v229, v229
	v_mfma_f32_16x16x32_bf16 v[104:107], v[136:139], v[4:7], v[0:3]
	v_exp_f32_e32 v230, v230
	v_add_f32_e32 v154, v228, v229
	v_mfma_f32_16x16x32_bf16 v[236:239], v[132:135], v[8:11], v[236:239]
	v_exp_f32_e32 v231, v231
	v_add_f32_e32 v154, v154, v230
	v_mfma_f32_16x16x32_bf16 v[104:107], v[140:143], v[8:11], v[104:107]
	v_exp_f32_e32 v232, v232
	v_add_f32_e32 v154, v154, v231
	v_mfma_f32_16x16x32_bf16 v[80:83], v[176:179], v[244:247], v[80:83]
	v_exp_f32_e32 v233, v233
	v_add_f32_e32 v154, v154, v232
	v_mfma_f32_16x16x32_bf16 v[76:79], v[180:183], v[244:247], v[76:79]
	v_exp_f32_e32 v234, v234
	v_add_f32_e32 v154, v154, v233
	v_cvt_pk_bf16_f32 v228, v228, v229
	v_mfma_f32_16x16x32_bf16 v[72:75], v[184:187], v[244:247], v[72:75]
	v_exp_f32_e32 v235, v235
	v_add_f32_e32 v154, v154, v234
	v_cvt_pk_bf16_f32 v229, v230, v231
	v_mfma_f32_16x16x32_bf16 v[68:71], v[188:191], v[244:247], v[68:71]
	v_cvt_pk_bf16_f32 v230, v232, v233
	v_cvt_pk_bf16_f32 v231, v234, v235
	v_add_f32_e32 v154, v154, v235
	v_add_f32_e32 v125, v125, v154
	v_mfma_f32_16x16x32_bf16 v[244:247], v[128:131], v[12:15], v[0:3]
	v_exp_f32_e32 v236, v236
	v_exp_f32_e32 v237, v237
	v_mfma_f32_16x16x32_bf16 v[248:251], v[136:139], v[12:15], v[0:3]
	v_exp_f32_e32 v238, v238
	v_add_f32_e32 v154, v236, v237
	v_mfma_f32_16x16x32_bf16 v[244:247], v[132:135], v[16:19], v[244:247]
	v_exp_f32_e32 v239, v239
	v_add_f32_e32 v154, v154, v238
	v_mfma_f32_16x16x32_bf16 v[248:251], v[140:143], v[16:19], v[248:251]
	v_exp_f32_e32 v104, v104
	v_add_f32_e32 v154, v154, v239
	v_mfma_f32_16x16x32_bf16 v[84:87], v[176:179], v[228:231], v[84:87]
	v_exp_f32_e32 v105, v105
	v_add_f32_e32 v154, v154, v104
	v_mfma_f32_16x16x32_bf16 v[92:95], v[180:183], v[228:231], v[92:95]
	v_exp_f32_e32 v106, v106
	v_add_f32_e32 v154, v154, v105
	v_cvt_pk_bf16_f32 v236, v236, v237
	v_mfma_f32_16x16x32_bf16 v[88:91], v[184:187], v[228:231], v[88:91]
	v_exp_f32_e32 v107, v107
	v_add_f32_e32 v154, v154, v106
	v_cvt_pk_bf16_f32 v237, v238, v239
	v_mfma_f32_16x16x32_bf16 v[96:99], v[188:191], v[228:231], v[96:99]
	v_cvt_pk_bf16_f32 v238, v104, v105
	v_cvt_pk_bf16_f32 v239, v106, v107
	v_add_f32_e32 v154, v154, v107
	v_add_f32_e32 v126, v126, v154
	s_waitcnt lgkmcnt(0)
; #define LAS __attribute__((address_space(3)))
; __device__ __forceinline__ s16x4 vtr(const LAS unsigned char* p) { return __builtin_bit_cast(s16x4, __builtin_amdgcn_ds_read_tr16_b64_v4i16((LAS v4i16_t*)p)); }
; __device__ __forceinline__ bf16x8 cat8(s16x4 a, s16x4 b) { return (bf16x8){a[0], a[1], a[2], a[3], b[0], b[1], b[2], b[3]}; }
; __device__ __forceinline__ bf16x8 pack8(const f32x4& a, const f32x4& b) { u32x4 w; w.x = pkbf(a[0], a[1]); w.y = pkbf(a[2], a[3]); w.z = pkbf(b[0], b[1]); w.w = pkbf(b[2], b[3]); return __builtin_bit_cast(bf16x8, w); }
; template <int NI> __device__ __forceinline__ void ring_wait() { asm volatile("s_waitcnt vmcnt(%0)" :: "n"(2 * NI) : "memory"); __syncthreads(); }
; __device__ __forceinline__ void drain_wait() { asm volatile("s_waitcnt vmcnt(0)" ::: "memory"); __syncthreads(); }
;     ...
;             ls[GPB * gh + gi] += exp_step<4>(S[gi]);
;             pf[gi][0] = pack8(S[gi][0], S[gi][1]); pf[gi][1] = pack8(S[gi][2], S[gi][3]);
;         }
; #pragma unroll
;         for (int kc = 0; kc < 2; ++kc)
; #pragma unroll
;             for (int db = 0; db < 4; ++db) {
;                 const LAS unsigned char* va = vrow + ((db ^ swz) << 5) + (32 * kc) * 128;
;                 const bf16x8 vf = cat8(vtr(va), vtr(va + 16 * 128));
; #pragma unroll
;                 for (int gi = 0; gi < GPB; ++gi) O[GPB * gh + gi][db] = __builtin_amdgcn_mfma_f32_16x16x32_bf16(vf, pf[gi][kc], O[GPB * gh + gi][db], 0, 0, 0);
; __device__ __forceinline__ void na_phase(LAS unsigned char* lds, const bf16_t* Q, const bf16_t* K, const bf16_t* V, bf16_t* Ob, const float* rpb, float negb) {
;     ...
;         const int r0w = min(max(r - 4, 0), 120);
;         drain_wait();
;         for (int t = 0; t < 4; ++t) {
;             dma_tile<2>(lds + ((t + 3) & 3) * NA_BUF, K, V, NA_ROW0(t + 3), DM, dl, w);
;             const LAS unsigned char* buf = lds + (t & 3) * NA_BUF;
;             full_tile<0, 1, 2>(O, ls, qf, negb, buf + hh * 8192, buf + 2 * 8192 + hh * 8192, lane, 0);
;             ring_wait<4>();
;         }
;         for (int t = 4; t < NT; ++t) {
;             dma_tile<2>(lds + ((t + 3) & 3) * NA_BUF, K, V, NA_ROW0(t + 3), DM, dl, w);
;             const LAS unsigned char* buf = lds + (t & 3) * NA_BUF;
;             const int kr = kr_lo + t - 4; const bool rv = kr >= r0w && kr < r0w + 8;
	v_mfma_f32_16x16x32_bf16 v[228:231], v[128:131], v[20:23], v[0:3]
	v_exp_f32_e32 v244, v244
	v_exp_f32_e32 v245, v245
	v_mfma_f32_16x16x32_bf16 v[232:235], v[136:139], v[20:23], v[0:3]
	v_exp_f32_e32 v246, v246
	v_add_f32_e32 v154, v244, v245
	v_mfma_f32_16x16x32_bf16 v[228:231], v[132:135], v[24:27], v[228:231]
	v_exp_f32_e32 v247, v247
	v_add_f32_e32 v154, v154, v246
	v_mfma_f32_16x16x32_bf16 v[232:235], v[140:143], v[24:27], v[232:235]
	v_exp_f32_e32 v248, v248
	v_add_f32_e32 v154, v154, v247
	v_mfma_f32_16x16x32_bf16 v[48:51], v[160:163], v[236:239], v[48:51]
	v_exp_f32_e32 v249, v249
	v_add_f32_e32 v154, v154, v248
	v_mfma_f32_16x16x32_bf16 v[44:47], v[164:167], v[236:239], v[44:47]
	v_exp_f32_e32 v250, v250
	v_add_f32_e32 v154, v154, v249
	v_cvt_pk_bf16_f32 v244, v244, v245
	v_mfma_f32_16x16x32_bf16 v[40:43], v[168:171], v[236:239], v[40:43]
	v_exp_f32_e32 v251, v251
	v_add_f32_e32 v154, v154, v250
	v_cvt_pk_bf16_f32 v245, v246, v247
	v_mfma_f32_16x16x32_bf16 v[36:39], v[172:175], v[236:239], v[36:39]
	v_cvt_pk_bf16_f32 v246, v248, v249
	v_cvt_pk_bf16_f32 v247, v250, v251
	v_add_f32_e32 v154, v154, v251
	v_add_f32_e32 v127, v127, v154
	v_mfma_f32_16x16x32_bf16 v[236:239], v[128:131], v[28:31], v[0:3]
	v_exp_f32_e32 v228, v228
	v_exp_f32_e32 v229, v229
	v_mfma_f32_16x16x32_bf16 v[104:107], v[136:139], v[28:31], v[0:3]
	v_exp_f32_e32 v230, v230
	v_add_f32_e32 v154, v228, v229
	v_mfma_f32_16x16x32_bf16 v[236:239], v[132:135], v[32:35], v[236:239]
	v_exp_f32_e32 v231, v231
	v_add_f32_e32 v154, v154, v230
	v_mfma_f32_16x16x32_bf16 v[104:107], v[140:143], v[32:35], v[104:107]
	v_exp_f32_e32 v232, v232
	v_add_f32_e32 v154, v154, v231
	v_mfma_f32_16x16x32_bf16 v[64:67], v[160:163], v[244:247], v[64:67]
	v_exp_f32_e32 v233, v233
	v_add_f32_e32 v154, v154, v232
	v_mfma_f32_16x16x32_bf16 v[60:63], v[164:167], v[244:247], v[60:63]
	v_exp_f32_e32 v234, v234
	v_add_f32_e32 v154, v154, v233
	v_cvt_pk_bf16_f32 v228, v228, v229
	v_mfma_f32_16x16x32_bf16 v[56:59], v[168:171], v[244:247], v[56:59]
	v_exp_f32_e32 v235, v235
	v_add_f32_e32 v154, v154, v234
	v_cvt_pk_bf16_f32 v229, v230, v231
	v_mfma_f32_16x16x32_bf16 v[52:55], v[172:175], v[244:247], v[52:55]
	v_cvt_pk_bf16_f32 v230, v232, v233
	v_cvt_pk_bf16_f32 v231, v234, v235
	v_add_f32_e32 v154, v154, v235
	v_add_f32_e32 v124, v124, v154
	v_mfma_f32_16x16x32_bf16 v[80:83], v[160:163], v[228:231], v[80:83]
	v_exp_f32_e32 v236, v236
	v_exp_f32_e32 v237, v237
	v_exp_f32_e32 v238, v238
	v_add_f32_e32 v154, v236, v237
	v_mfma_f32_16x16x32_bf16 v[76:79], v[164:167], v[228:231], v[76:79]
	v_exp_f32_e32 v239, v239
	v_add_f32_e32 v154, v154, v238
	v_exp_f32_e32 v104, v104
	v_add_f32_e32 v154, v154, v239
	v_mfma_f32_16x16x32_bf16 v[72:75], v[168:171], v[228:231], v[72:75]
	v_exp_f32_e32 v105, v105
	v_add_f32_e32 v154, v154, v104
	v_exp_f32_e32 v106, v106
	v_add_f32_e32 v154, v154, v105
	v_cvt_pk_bf16_f32 v236, v236, v237
	v_mfma_f32_16x16x32_bf16 v[68:71], v[172:175], v[228:231], v[68:71]
	v_exp_f32_e32 v107, v107
	v_add_f32_e32 v154, v154, v106
	v_cvt_pk_bf16_f32 v237, v238, v239
	v_cvt_pk_bf16_f32 v238, v104, v105
	v_cvt_pk_bf16_f32 v239, v106, v107
	v_add_f32_e32 v154, v154, v107
	v_add_f32_e32 v125, v125, v154
	v_mfma_f32_16x16x32_bf16 v[84:87], v[160:163], v[236:239], v[84:87]
	v_mfma_f32_16x16x32_bf16 v[92:95], v[164:167], v[236:239], v[92:95]
	v_mfma_f32_16x16x32_bf16 v[88:91], v[168:171], v[236:239], v[88:91]
	v_mfma_f32_16x16x32_bf16 v[96:99], v[172:175], v[236:239], v[96:99]
	s_add_i32 vcc_lo, vcc_lo, 0x8000
	s_add_u32 s94, s94, 64
	s_addc_u32 s95, s95, 0
	s_add_i32 s96, s96, 1
	s_waitcnt vmcnt(8)
	s_barrier
	s_cmp_lt_i32 s93, 5
	s_cbranch_scc1 .LBB0_361
	s_add_i32 s97, s97, -4
	s_min_u32 s94, s97, 0x78
	s_add_i32 s95, s94, 8
	s_add_i32 s96, s93, -4
	s_cmp_gt_u32 s68, 4
	s_cselect_b32 s7, 0, 0
	s_cselect_b32 s6, s68, 4
	s_lshl_b64 s[6:7], s[6:7], 6
	s_add_u32 s6, s6, s61
	s_addc_u32 s7, s7, 0
	s_add_u32 s59, s6, 0xffffffc0
	s_addc_u32 s66, s7, -1
	s_add_i32 s7, s2, s68
	s_mul_i32 s6, s60, 0x7c
	s_mulk_i32 s7, 0x7c
	s_sub_i32 s6, s6, s7
	s_mov_b32 s97, 0
	v_add_u32_e32 v128, s6, v219
	s_add_i32 s68, s60, -4
	v_add_u32_e32 v129, s6, v220
	s_mov_b32 s6, 0x20000
	v_mov_b32_e32 v253, 0xffff
	v_mov_b32_e32 v254, 0xffff0000
	v_cndmask_b32_e64 v225, 0, v253, s[8:9]
	v_cndmask_b32_e64 v255, 0, v254, s[10:11]
	v_cndmask_b32_e64 v226, 0, v253, s[12:13]
	v_or_b32_e32 v225, v225, v255
	v_cndmask_b32_e64 v255, 0, v254, s[14:15]
	s_nop 0
	v_or_b32_e32 v226, v226, v255
	v_cndmask_b32_e64 v227, 0, v253, s[24:25]
	v_cndmask_b32_e64 v255, 0, v254, s[26:27]
	v_cndmask_b32_e64 v242, 0, v253, s[28:29]
	v_or_b32_e32 v227, v227, v255
	v_cndmask_b32_e64 v255, 0, v254, s[30:31]
	s_nop 0
	v_or_b32_e32 v242, v242, v255
	v_cndmask_b32_e64 v243, 0, v253, s[42:43]
	v_cndmask_b32_e64 v255, 0, v254, s[44:45]
	v_cndmask_b32_e64 v252, 0, v253, s[46:47]
	v_or_b32_e32 v243, v243, v255
	v_cndmask_b32_e64 v255, 0, v254, s[48:49]
	s_nop 0
	v_or_b32_e32 v252, v252, v255
	s_branch .LBB0_383

; #define LAS __attribute__((address_space(3)))
; __device__ __forceinline__ void na_local_tile(f32x4 (&O)[4][4], float (&ls)[4], const bf16x8 (&qf)[4][2], float negb,
;                                               const LAS unsigned char* Kt, const LAS unsigned char* Vt, int lane, const LAS float* bias_row, bool rowvalid) {
;     const int l15 = lane & 15, g = lane >> 4, q4 = l15 >> 2;
;     const LAS unsigned char* kb0 = Kt + l15 * 128;
;     const int kx0 = ((g) ^ (l15 & 7)) << 4, kx1 = ((4 + g) ^ (l15 & 7)) << 4;
;     const LAS unsigned char* vrow = Vt + (4 * g + q4) * 128 + (lane & 3) * 8;
;     const int swz = (2 * (g & 1) + (q4 >> 1)) & 3;
; #pragma unroll
;     for (int grp = 0; grp < 4; ++grp) {
;         const int kwin = grp == 0 ? 0 : (grp == 1 ? 8 : (grp == 2 ? 24 : 32));
;         f32x4 S[2];
; #pragma unroll
;         for (int k2 = 0; k2 < 2; ++k2) {
;             const bf16x8 kf0 = *(const LAS bf16x8*)(kb0 + (kwin + 16 * k2) * 128 + kx0), kf1 = *(const LAS bf16x8*)(kb0 + (kwin + 16 * k2) * 128 + kx1);
;             S[k2] = __builtin_amdgcn_mfma_f32_16x16x32_bf16(kf0, qf[grp][0], (f32x4){negb, negb, negb, negb}, 0, 0, 0);
;             S[k2] = __builtin_amdgcn_mfma_f32_16x16x32_bf16(kf1, qf[grp][1], S[k2], 0, 0, 0); }
;         const int c = 16 * grp + l15; const int c0 = rowvalid ? min(max(c - 8, 0), 48) : 4096;
;         const LAS float* bl = bias_row + (15 - c + 4 * g);
; #pragma unroll
;         for (int k2 = 0; k2 < 2; ++k2)
; #pragma unroll
;             for (int i = 0; i < 4; ++i) { const int kc = kwin + 16 * k2 + 4 * g + i; const float bias = bl[kwin + 16 * k2 + i];
;                 S[k2][i] = ((unsigned)(kc - c0) < 16u) ? S[k2][i] + bias : NEGBIG; }
;         ls[grp] += exp_step<2>(S);
;         const bf16x8 pf = pack8(S[0], S[1]);
; __device__ __forceinline__ void na_phase(LAS unsigned char* lds, const bf16_t* Q, const bf16_t* K, const bf16_t* V, bf16_t* Ob, const float* rpb, float negb) {
;     ...
;         for (int t = 4; t < NT; ++t) {
;             dma_tile<2>(lds + ((t + 3) & 3) * NA_BUF, K, V, NA_ROW0(t + 3), DM, dl, w);
;             const LAS unsigned char* buf = lds + (t & 3) * NA_BUF;
;             const int kr = kr_lo + t - 4; const bool rv = kr >= r0w && kr < r0w + 8;
;             if (rv) na_local_tile(O, ls, qf, negb, buf + hh * 8192, buf + 2 * 8192 + hh * 8192, lane, tab + hh * 512 + (kr - r + 7) * 31, true);
.LBB0_383:
	s_add_i32 s60, s6, 0x18000
	s_and_b32 s60, s60, 0x18000
	s_add_i32 s7, s97, 7
	s_add_i32 vcc_lo, s60, 0
	s_cmp_lt_i32 s7, s93
	s_cselect_b32 s61, s66, 0
	s_cselect_b32 s60, s59, s82
	s_lshl_b64 s[60:61], s[60:61], 11
	s_add_u32 s76, s67, s60
	s_addc_u32 s77, s4, s61
	s_add_u32 s60, s5, s60
	s_addc_u32 s61, s58, s61
	s_add_i32 s7, s63, vcc_lo
	s_add_i32 vcc_lo, s7, 0x4000
	s_mov_b32 vcc_hi, m0
	s_mov_b32 m0, s7
	s_nop 0
	global_load_lds_dwordx4 v221, s[76:77]
	s_mov_b32 m0, vcc_hi
	s_nop 0
	s_mov_b32 vcc_hi, m0
	s_mov_b32 m0, vcc_lo
	s_nop 0
	global_load_lds_dwordx4 v222, s[60:61]
	s_mov_b32 m0, vcc_hi
	s_add_i32 vcc_lo, s7, 0x2000
	s_mov_b32 vcc_hi, m0
	s_mov_b32 m0, vcc_lo
	s_nop 0
	global_load_lds_dwordx4 v223, s[76:77]
	s_mov_b32 m0, vcc_hi
	s_addk_i32 s7, 0x6000
	s_mov_b32 s76, m0
	s_mov_b32 m0, s7
	s_nop 0
	global_load_lds_dwordx4 v224, s[60:61]
	s_mov_b32 m0, s76
	s_add_i32 s7, s68, s97
	s_cmp_ge_u32 s7, s94
	s_cselect_b64 s[60:61], -1, 0
	s_cmp_lt_u32 s7, s95
	s_cselect_b64 s[76:77], -1, 0
	s_and_b64 s[60:61], s[60:61], s[76:77]
	s_andn2_b64 vcc, exec, s[60:61]
	s_cbranch_vccnz .LBB0_382
	s_and_b32 s7, s6, 0x18000
	s_add_i32 s7, s65, s7
	s_mov_b32 s76, 0x20000
	v_add3_u32 v236, v129, v110, s76
	v_add_u32_e32 v130, s7, v111
	v_add3_u32 v235, s7, v210, v205
	ds_read2_b32 v[100:101], v236 offset0:108 offset1:109
	ds_read2_b32 v[102:103], v236 offset0:110 offset1:111
	ds_read2_b32 v[104:105], v236 offset0:124 offset1:125
	ds_read2_b32 v[106:107], v236 offset0:126 offset1:127
	v_add_u32_e32 v131, v130, v204
	v_add_u32_e32 v130, v130, v203
	ds_read2_b32 v[140:141], v236 offset0:100 offset1:101
	ds_read2_b32 v[142:143], v236 offset0:102 offset1:103
	ds_read2_b32 v[144:145], v236 offset0:116 offset1:117
	ds_read2_b32 v[146:147], v236 offset0:118 offset1:119
	ds_read2_b32 v[148:149], v236 offset0:92 offset1:93
	ds_read2_b32 v[150:151], v236 offset0:94 offset1:95
	ds_read_b128 v[160:163], v130
	ds_read_b128 v[164:167], v131
	ds_read_b128 v[168:171], v130 offset:2048
	ds_read_b128 v[172:175], v131 offset:2048
	v_add_u32_e32 v232, v235, v206
	v_add_u32_e32 v233, v235, v207
	v_add_u32_e32 v234, v235, v208
	v_add_u32_e32 v235, v235, v209
	s_waitcnt lgkmcnt(4)
	ds_read2_b32 v[228:229], v236 offset0:108 offset1:109
	ds_read2_b32 v[230:231], v236 offset0:110 offset1:111
	ds_read_b128 v[176:179], v130 offset:1024
	ds_read_b128 v[180:183], v131 offset:1024
	ds_read_b128 v[184:187], v130 offset:3072
	ds_read_b128 v[188:191], v131 offset:3072
	s_waitcnt lgkmcnt(6)
	v_mfma_f32_16x16x32_bf16 v[100:103], v[160:163], v[4:7], v[100:103]
	v_mfma_f32_16x16x32_bf16 v[104:107], v[168:171], v[4:7], v[104:107]
	v_mfma_f32_16x16x32_bf16 v[100:103], v[164:167], v[8:11], v[100:103]
	v_mfma_f32_16x16x32_bf16 v[104:107], v[172:175], v[8:11], v[104:107]
	ds_read_b64_tr_b16 v[160:161], v232 offset:16384
	ds_read_b64_tr_b16 v[162:163], v232 offset:18432
	ds_read_b64_tr_b16 v[164:165], v233 offset:16384
	ds_read_b64_tr_b16 v[166:167], v233 offset:18432
	ds_read_b64_tr_b16 v[168:169], v234 offset:16384
	ds_read_b64_tr_b16 v[170:171], v234 offset:18432
	ds_read_b64_tr_b16 v[172:173], v235 offset:16384
	ds_read_b64_tr_b16 v[174:175], v235 offset:18432
	s_waitcnt lgkmcnt(8)
	v_mfma_f32_16x16x32_bf16 v[132:135], v[176:179], v[12:15], v[140:143]
	v_mfma_f32_16x16x32_bf16 v[136:139], v[184:187], v[12:15], v[144:147]
	v_mfma_f32_16x16x32_bf16 v[132:135], v[180:183], v[16:19], v[132:135]
	v_mfma_f32_16x16x32_bf16 v[136:139], v[188:191], v[16:19], v[136:139]
	v_cndmask_b32_e64 v100, v104, v100, s[8:9]
	v_cndmask_b32_e64 v101, v105, v101, s[10:11]
	v_cndmask_b32_e64 v102, v106, v102, s[12:13]
	v_cndmask_b32_e64 v103, v107, v103, s[14:15]
	v_exp_f32_e32 v100, v100
	v_exp_f32_e32 v101, v101
	v_exp_f32_e32 v102, v102
	v_add_f32_e32 v154, v100, v101
	v_exp_f32_e32 v103, v103
	v_add_f32_e32 v154, v154, v102
	v_cvt_pk_bf16_f32 v104, v100, v101
	v_add_f32_e32 v154, v154, v103
	v_cvt_pk_bf16_f32 v105, v102, v103
	v_and_b32_e32 v100, v104, v225
	v_and_b32_e32 v101, v105, v226
	v_xor_b32_e32 v102, v104, v100
	v_xor_b32_e32 v103, v105, v101
	v_add_f32_e32 v126, v126, v154
	s_waitcnt lgkmcnt(0)
; #define LAS __attribute__((address_space(3)))
; __device__ __forceinline__ s16x4 vtr(const LAS unsigned char* p) { return __builtin_bit_cast(s16x4, __builtin_amdgcn_ds_read_tr16_b64_v4i16((LAS v4i16_t*)p)); }
; __device__ __forceinline__ bf16x8 cat8(s16x4 a, s16x4 b) { return (bf16x8){a[0], a[1], a[2], a[3], b[0], b[1], b[2], b[3]}; }
; __device__ __forceinline__ bf16x8 pack8(const f32x4& a, const f32x4& b) { u32x4 w; w.x = pkbf(a[0], a[1]); w.y = pkbf(a[2], a[3]); w.z = pkbf(b[0], b[1]); w.w = pkbf(b[2], b[3]); return __builtin_bit_cast(bf16x8, w); }
; __device__ __forceinline__ void na_local_tile(f32x4 (&O)[4][4], float (&ls)[4], const bf16x8 (&qf)[4][2], float negb,
;                                               const LAS unsigned char* Kt, const LAS unsigned char* Vt, int lane, const LAS float* bias_row, bool rowvalid) {
;     ...
;     for (int grp = 0; grp < 4; ++grp) {
;         const int kwin = grp == 0 ? 0 : (grp == 1 ? 8 : (grp == 2 ? 24 : 32));
;         f32x4 S[2];
; #pragma unroll
;         for (int k2 = 0; k2 < 2; ++k2) {
;             const bf16x8 kf0 = *(const LAS bf16x8*)(kb0 + (kwin + 16 * k2) * 128 + kx0), kf1 = *(const LAS bf16x8*)(kb0 + (kwin + 16 * k2) * 128 + kx1);
;             S[k2] = __builtin_amdgcn_mfma_f32_16x16x32_bf16(kf0, qf[grp][0], (f32x4){negb, negb, negb, negb}, 0, 0, 0);
;             S[k2] = __builtin_amdgcn_mfma_f32_16x16x32_bf16(kf1, qf[grp][1], S[k2], 0, 0, 0); }
;         const int c = 16 * grp + l15; const int c0 = rowvalid ? min(max(c - 8, 0), 48) : 4096;
;         const LAS float* bl = bias_row + (15 - c + 4 * g);
; #pragma unroll
;         for (int k2 = 0; k2 < 2; ++k2)
; #pragma unroll
;             for (int i = 0; i < 4; ++i) { const int kc = kwin + 16 * k2 + 4 * g + i; const float bias = bl[kwin + 16 * k2 + i];
;                 S[k2][i] = ((unsigned)(kc - c0) < 16u) ? S[k2][i] + bias : NEGBIG; }
;         ls[grp] += exp_step<2>(S);
;         const bf16x8 pf = pack8(S[0], S[1]);
; #pragma unroll
;         for (int db = 0; db < 4; ++db) {
;             const LAS unsigned char* va = vrow + ((db ^ swz) << 5) + kwin * 128;
;             const bf16x8 vf = cat8(vtr(va), vtr(va + 16 * 128));
;             O[grp][db] = __builtin_amdgcn_mfma_f32_16x16x32_bf16(vf, pf, O[grp][db], 0, 0, 0);
;         }
;         __builtin_amdgcn_sched_barrier(0x108);
	v_mfma_f32_16x16x32_bf16 v[48:51], v[160:163], v[100:103], v[48:51]
	v_mfma_f32_16x16x32_bf16 v[44:47], v[164:167], v[100:103], v[44:47]
	v_mfma_f32_16x16x32_bf16 v[40:43], v[168:171], v[100:103], v[40:43]
	v_mfma_f32_16x16x32_bf16 v[36:39], v[172:175], v[100:103], v[36:39]
	ds_read_b128 v[160:163], v130 offset:3072
	ds_read_b128 v[164:167], v131 offset:3072
	ds_read_b128 v[168:171], v130 offset:5120
	ds_read_b128 v[172:175], v131 offset:5120
	ds_read_b64_tr_b16 v[176:177], v232 offset:17408
	ds_read_b64_tr_b16 v[178:179], v232 offset:19456
	ds_read_b64_tr_b16 v[180:181], v233 offset:17408
	ds_read_b64_tr_b16 v[182:183], v233 offset:19456
	ds_read_b64_tr_b16 v[184:185], v234 offset:17408
	ds_read_b64_tr_b16 v[186:187], v234 offset:19456
	ds_read_b64_tr_b16 v[188:189], v235 offset:17408
	ds_read_b64_tr_b16 v[190:191], v235 offset:19456
	v_cndmask_b32_e64 v132, v136, v132, s[24:25]
	v_cndmask_b32_e64 v133, v137, v133, s[26:27]
	v_cndmask_b32_e64 v134, v138, v134, s[28:29]
	v_cndmask_b32_e64 v135, v139, v135, s[30:31]
	v_exp_f32_e32 v132, v132
	v_exp_f32_e32 v133, v133
	v_exp_f32_e32 v134, v134
	v_add_f32_e32 v154, v132, v133
	v_exp_f32_e32 v135, v135
	v_add_f32_e32 v154, v154, v134
	v_cvt_pk_bf16_f32 v136, v132, v133
	v_add_f32_e32 v154, v154, v135
	v_cvt_pk_bf16_f32 v137, v134, v135
	v_and_b32_e32 v132, v136, v227
	v_and_b32_e32 v133, v137, v242
	v_xor_b32_e32 v134, v136, v132
	v_xor_b32_e32 v135, v137, v133
	v_add_f32_e32 v127, v127, v154
	s_waitcnt lgkmcnt(0)
	v_mfma_f32_16x16x32_bf16 v[64:67], v[176:179], v[132:135], v[64:67]
	v_mfma_f32_16x16x32_bf16 v[60:63], v[180:183], v[132:135], v[60:63]
	v_mfma_f32_16x16x32_bf16 v[56:59], v[184:187], v[132:135], v[56:59]
	v_mfma_f32_16x16x32_bf16 v[52:55], v[188:191], v[132:135], v[52:55]
	v_mfma_f32_16x16x32_bf16 v[140:143], v[160:163], v[20:23], v[140:143]
	v_mfma_f32_16x16x32_bf16 v[144:147], v[168:171], v[20:23], v[144:147]
	v_mfma_f32_16x16x32_bf16 v[140:143], v[164:167], v[24:27], v[140:143]
	v_mfma_f32_16x16x32_bf16 v[144:147], v[172:175], v[24:27], v[144:147]
	ds_read_b128 v[176:179], v130 offset:4096
	ds_read_b128 v[180:183], v131 offset:4096
	ds_read_b128 v[184:187], v130 offset:6144
	ds_read_b128 v[188:191], v131 offset:6144
	ds_read_b64_tr_b16 v[160:161], v232 offset:19456
	ds_read_b64_tr_b16 v[162:163], v232 offset:21504
	ds_read_b64_tr_b16 v[164:165], v233 offset:19456
	ds_read_b64_tr_b16 v[166:167], v233 offset:21504
	ds_read_b64_tr_b16 v[168:169], v234 offset:19456
	ds_read_b64_tr_b16 v[170:171], v234 offset:21504
	ds_read_b64_tr_b16 v[172:173], v235 offset:19456
	ds_read_b64_tr_b16 v[174:175], v235 offset:21504
	v_cndmask_b32_e64 v140, v144, v140, s[24:25]
	v_cndmask_b32_e64 v141, v145, v141, s[26:27]
	v_cndmask_b32_e64 v142, v146, v142, s[28:29]
	v_cndmask_b32_e64 v143, v147, v143, s[30:31]
	v_exp_f32_e32 v140, v140
	v_exp_f32_e32 v141, v141
	v_exp_f32_e32 v142, v142
	v_add_f32_e32 v154, v140, v141
	v_exp_f32_e32 v143, v143
	v_add_f32_e32 v154, v154, v142
	v_cvt_pk_bf16_f32 v144, v140, v141
	v_add_f32_e32 v154, v154, v143
	v_cvt_pk_bf16_f32 v145, v142, v143
	v_and_b32_e32 v140, v144, v227
	v_and_b32_e32 v141, v145, v242
	v_xor_b32_e32 v142, v144, v140
	v_xor_b32_e32 v143, v145, v141
	v_add_f32_e32 v124, v124, v154
	s_waitcnt lgkmcnt(8)
	v_mfma_f32_16x16x32_bf16 v[148:151], v[176:179], v[28:31], v[148:151]
	v_mfma_f32_16x16x32_bf16 v[228:231], v[184:187], v[28:31], v[228:231]
	v_mfma_f32_16x16x32_bf16 v[148:151], v[180:183], v[32:35], v[148:151]
	v_mfma_f32_16x16x32_bf16 v[228:231], v[188:191], v[32:35], v[228:231]
	s_waitcnt lgkmcnt(0)
	v_mfma_f32_16x16x32_bf16 v[80:83], v[160:163], v[140:143], v[80:83]
	v_mfma_f32_16x16x32_bf16 v[76:79], v[164:167], v[140:143], v[76:79]
	v_mfma_f32_16x16x32_bf16 v[72:75], v[168:171], v[140:143], v[72:75]
	v_mfma_f32_16x16x32_bf16 v[68:71], v[172:175], v[140:143], v[68:71]
	ds_read_b64_tr_b16 v[176:177], v232 offset:20480
	ds_read_b64_tr_b16 v[178:179], v232 offset:22528
	ds_read_b64_tr_b16 v[180:181], v233 offset:20480
	ds_read_b64_tr_b16 v[182:183], v233 offset:22528
	ds_read_b64_tr_b16 v[184:185], v234 offset:20480
	ds_read_b64_tr_b16 v[186:187], v234 offset:22528
	ds_read_b64_tr_b16 v[188:189], v235 offset:20480
	ds_read_b64_tr_b16 v[190:191], v235 offset:22528
	v_cndmask_b32_e64 v148, v228, v148, s[42:43]
	v_cndmask_b32_e64 v149, v229, v149, s[44:45]
	v_cndmask_b32_e64 v150, v230, v150, s[46:47]
	v_cndmask_b32_e64 v151, v231, v151, s[48:49]
	v_exp_f32_e32 v148, v148
	v_exp_f32_e32 v149, v149
	v_exp_f32_e32 v150, v150
	v_add_f32_e32 v154, v148, v149
	v_exp_f32_e32 v151, v151
	v_add_f32_e32 v154, v154, v150
	v_cvt_pk_bf16_f32 v228, v148, v149
	v_add_f32_e32 v154, v154, v151
	v_cvt_pk_bf16_f32 v229, v150, v151
	v_and_b32_e32 v148, v228, v243
	v_and_b32_e32 v149, v229, v252
	v_xor_b32_e32 v150, v228, v148
	v_xor_b32_e32 v151, v229, v149
	v_add_f32_e32 v125, v125, v154
	s_waitcnt lgkmcnt(0)
	v_mfma_f32_16x16x32_bf16 v[84:87], v[176:179], v[148:151], v[84:87]
	v_mfma_f32_16x16x32_bf16 v[92:95], v[180:183], v[148:151], v[92:95]
	v_mfma_f32_16x16x32_bf16 v[88:91], v[184:187], v[148:151], v[88:91]
	v_mfma_f32_16x16x32_bf16 v[96:99], v[188:191], v[148:151], v[96:99]
	s_branch .LBB0_382
